# RWKV scan consumer: the step's LDS reads issued as one burst before the dependent p chain
# speedup vs baseline: 1.0193x; 1.0100x over previous
.LBB0_1750:
	s_and_b32 s23, s22, 1
	s_mul_i32 s2, s23, 0xc000
	s_add_i32 s2, s2, 0
	v_add_u32_e32 v20, s2, v10
	s_add_i32 s2, s2, s5
	v_lshl_add_u32 v21, v1, 2, s2
	ds_read_b128 v[36:39], v20 offset:0
	ds_read_b128 v[40:43], v20 offset:8192
	ds_read_b64 v[56:57], v21 offset:40960
	ds_read_b128 v[48:51], v20 offset:24576
	ds_read_b128 v[44:47], v20 offset:16384
	ds_read_b128 v[52:55], v20 offset:32768
	s_waitcnt lgkmcnt(0)
	ds_read_b128 v[60:63], v20 offset:256
	ds_read_b128 v[64:67], v20 offset:8448
	ds_read_b64 v[80:81], v21 offset:41216
	ds_read_b128 v[72:75], v20 offset:24832
	ds_read_b128 v[68:71], v20 offset:16640
	v_pk_mul_f32 v[22:23], v[2:3], v[36:37] op_sel:[0,0] op_sel_hi:[1,0]
	v_pk_fma_f32 v[22:23], v[4:5], v[36:37], v[22:23] op_sel:[0,1,0] op_sel_hi:[1,1,1]
	v_pk_fma_f32 v[22:23], v[6:7], v[38:39], v[22:23] op_sel:[0,0,0] op_sel_hi:[1,0,1]
	v_pk_fma_f32 v[22:23], v[8:9], v[38:39], v[22:23] op_sel:[0,1,0] op_sel_hi:[1,1,1]
	ds_read_b128 v[76:79], v20 offset:33024
	s_nop 0
	v_add_f32_dpp v22, v22, v22 quad_perm:[1,0,3,2] row_mask:0xf bank_mask:0xf
	v_add_f32_dpp v23, v23, v23 quad_perm:[1,0,3,2] row_mask:0xf bank_mask:0xf
	v_pk_mul_f32 v[84:85], v[2:3], v[40:41] op_sel:[0,0] op_sel_hi:[1,0]
	v_pk_mul_f32 v[86:87], v[4:5], v[40:41] op_sel:[0,1] op_sel_hi:[1,1]
	v_add_f32_dpp v22, v22, v22 quad_perm:[2,3,0,1] row_mask:0xf bank_mask:0xf
	v_add_f32_dpp v23, v23, v23 quad_perm:[2,3,0,1] row_mask:0xf bank_mask:0xf
	v_pk_mul_f32 v[88:89], v[6:7], v[42:43] op_sel:[0,0] op_sel_hi:[1,0]
	v_pk_mul_f32 v[90:91], v[8:9], v[42:43] op_sel:[0,1] op_sel_hi:[1,1]
	v_add_f32_dpp v22, v22, v22 row_half_mirror row_mask:0xf bank_mask:0xf
	v_add_f32_dpp v23, v23, v23 row_half_mirror row_mask:0xf bank_mask:0xf
	v_pk_fma_f32 v[84:85], v[48:49], v[56:57], v[84:85] op_sel:[0,0,0] op_sel_hi:[0,1,1]
	v_pk_fma_f32 v[86:87], v[48:49], v[56:57], v[86:87] op_sel:[1,0,0] op_sel_hi:[1,1,1]
	v_add_f32_dpp v22, v22, v22 row_mirror row_mask:0xf bank_mask:0xf
	v_add_f32_dpp v23, v23, v23 row_mirror row_mask:0xf bank_mask:0xf
	v_pk_fma_f32 v[88:89], v[50:51], v[56:57], v[88:89] op_sel:[0,0,0] op_sel_hi:[0,1,1]
	v_pk_fma_f32 v[90:91], v[50:51], v[56:57], v[90:91] op_sel:[1,0,0] op_sel_hi:[1,1,1]
	v_pk_fma_f32 v[2:3], v[44:45], v[22:23], v[84:85] op_sel:[0,0,0] op_sel_hi:[0,1,1] neg_lo:[1,0,0] neg_hi:[1,0,0]
	v_pk_fma_f32 v[4:5], v[44:45], v[22:23], v[86:87] op_sel:[1,0,0] op_sel_hi:[1,1,1] neg_lo:[1,0,0] neg_hi:[1,0,0]
	v_pk_fma_f32 v[6:7], v[46:47], v[22:23], v[88:89] op_sel:[0,0,0] op_sel_hi:[0,1,1] neg_lo:[1,0,0] neg_hi:[1,0,0]
	v_pk_fma_f32 v[8:9], v[46:47], v[22:23], v[90:91] op_sel:[1,0,0] op_sel_hi:[1,1,1] neg_lo:[1,0,0] neg_hi:[1,0,0]
	s_waitcnt lgkmcnt(0)
	ds_read_b128 v[36:39], v20 offset:512
	ds_read_b128 v[40:43], v20 offset:8704
	ds_read_b64 v[56:57], v21 offset:41472
	ds_read_b128 v[48:51], v20 offset:25088
	ds_read_b128 v[44:47], v20 offset:16896
	v_pk_mul_f32 v[22:23], v[2:3], v[60:61] op_sel:[0,0] op_sel_hi:[1,0]
	v_pk_mul_f32 v[24:25], v[2:3], v[52:53] op_sel:[0,0] op_sel_hi:[1,0]
	v_pk_fma_f32 v[22:23], v[4:5], v[60:61], v[22:23] op_sel:[0,1,0] op_sel_hi:[1,1,1]
	v_pk_fma_f32 v[24:25], v[4:5], v[52:53], v[24:25] op_sel:[0,1,0] op_sel_hi:[1,1,1]
	v_pk_fma_f32 v[22:23], v[6:7], v[62:63], v[22:23] op_sel:[0,0,0] op_sel_hi:[1,0,1]
	v_pk_fma_f32 v[24:25], v[6:7], v[54:55], v[24:25] op_sel:[0,0,0] op_sel_hi:[1,0,1]
	v_pk_fma_f32 v[22:23], v[8:9], v[62:63], v[22:23] op_sel:[0,1,0] op_sel_hi:[1,1,1]
	v_pk_fma_f32 v[24:25], v[8:9], v[54:55], v[24:25] op_sel:[0,1,0] op_sel_hi:[1,1,1]
	ds_read_b128 v[52:55], v20 offset:33280
	v_add_f32_dpp v22, v22, v22 quad_perm:[1,0,3,2] row_mask:0xf bank_mask:0xf
	v_add_f32_dpp v23, v23, v23 quad_perm:[1,0,3,2] row_mask:0xf bank_mask:0xf
	v_pk_mul_f32 v[84:85], v[2:3], v[64:65] op_sel:[0,0] op_sel_hi:[1,0]
	v_pk_mul_f32 v[86:87], v[4:5], v[64:65] op_sel:[0,1] op_sel_hi:[1,1]
	v_add_f32_dpp v22, v22, v22 quad_perm:[2,3,0,1] row_mask:0xf bank_mask:0xf
	v_add_f32_dpp v23, v23, v23 quad_perm:[2,3,0,1] row_mask:0xf bank_mask:0xf
	v_pk_mul_f32 v[88:89], v[6:7], v[66:67] op_sel:[0,0] op_sel_hi:[1,0]
	v_pk_mul_f32 v[90:91], v[8:9], v[66:67] op_sel:[0,1] op_sel_hi:[1,1]
	v_add_f32_dpp v22, v22, v22 row_half_mirror row_mask:0xf bank_mask:0xf
	v_add_f32_dpp v23, v23, v23 row_half_mirror row_mask:0xf bank_mask:0xf
	v_pk_fma_f32 v[84:85], v[72:73], v[80:81], v[84:85] op_sel:[0,0,0] op_sel_hi:[0,1,1]
	v_pk_fma_f32 v[86:87], v[72:73], v[80:81], v[86:87] op_sel:[1,0,0] op_sel_hi:[1,1,1]
	v_add_f32_dpp v22, v22, v22 row_mirror row_mask:0xf bank_mask:0xf
	v_add_f32_dpp v23, v23, v23 row_mirror row_mask:0xf bank_mask:0xf
	v_pk_fma_f32 v[88:89], v[74:75], v[80:81], v[88:89] op_sel:[0,0,0] op_sel_hi:[0,1,1]
	v_pk_fma_f32 v[90:91], v[74:75], v[80:81], v[90:91] op_sel:[1,0,0] op_sel_hi:[1,1,1]
	v_pk_fma_f32 v[2:3], v[68:69], v[22:23], v[84:85] op_sel:[0,0,0] op_sel_hi:[0,1,1] neg_lo:[1,0,0] neg_hi:[1,0,0]
	v_pk_fma_f32 v[4:5], v[68:69], v[22:23], v[86:87] op_sel:[1,0,0] op_sel_hi:[1,1,1] neg_lo:[1,0,0] neg_hi:[1,0,0]
	v_pk_fma_f32 v[6:7], v[70:71], v[22:23], v[88:89] op_sel:[0,0,0] op_sel_hi:[0,1,1] neg_lo:[1,0,0] neg_hi:[1,0,0]
	v_pk_fma_f32 v[8:9], v[70:71], v[22:23], v[90:91] op_sel:[1,0,0] op_sel_hi:[1,1,1] neg_lo:[1,0,0] neg_hi:[1,0,0]
	s_waitcnt lgkmcnt(0)
	ds_read_b128 v[60:63], v20 offset:768
	ds_read_b128 v[64:67], v20 offset:8960
	ds_read_b64 v[80:81], v21 offset:41728
	ds_read_b128 v[72:75], v20 offset:25344
	ds_read_b128 v[68:71], v20 offset:17152
	v_pk_mul_f32 v[22:23], v[2:3], v[36:37] op_sel:[0,0] op_sel_hi:[1,0]
	v_pk_mul_f32 v[26:27], v[2:3], v[76:77] op_sel:[0,0] op_sel_hi:[1,0]
	v_pk_fma_f32 v[22:23], v[4:5], v[36:37], v[22:23] op_sel:[0,1,0] op_sel_hi:[1,1,1]
	v_pk_fma_f32 v[26:27], v[4:5], v[76:77], v[26:27] op_sel:[0,1,0] op_sel_hi:[1,1,1]
	v_pk_fma_f32 v[22:23], v[6:7], v[38:39], v[22:23] op_sel:[0,0,0] op_sel_hi:[1,0,1]
	v_pk_fma_f32 v[26:27], v[6:7], v[78:79], v[26:27] op_sel:[0,0,0] op_sel_hi:[1,0,1]
	v_pk_fma_f32 v[22:23], v[8:9], v[38:39], v[22:23] op_sel:[0,1,0] op_sel_hi:[1,1,1]
	v_pk_fma_f32 v[26:27], v[8:9], v[78:79], v[26:27] op_sel:[0,1,0] op_sel_hi:[1,1,1]
	ds_read_b128 v[76:79], v20 offset:33536
	v_add_f32_dpp v22, v22, v22 quad_perm:[1,0,3,2] row_mask:0xf bank_mask:0xf
	v_add_f32_dpp v23, v23, v23 quad_perm:[1,0,3,2] row_mask:0xf bank_mask:0xf
	v_pk_mul_f32 v[84:85], v[2:3], v[40:41] op_sel:[0,0] op_sel_hi:[1,0]
	v_pk_mul_f32 v[86:87], v[4:5], v[40:41] op_sel:[0,1] op_sel_hi:[1,1]
	v_add_f32_dpp v22, v22, v22 quad_perm:[2,3,0,1] row_mask:0xf bank_mask:0xf
	v_add_f32_dpp v23, v23, v23 quad_perm:[2,3,0,1] row_mask:0xf bank_mask:0xf
	v_pk_mul_f32 v[88:89], v[6:7], v[42:43] op_sel:[0,0] op_sel_hi:[1,0]
	v_pk_mul_f32 v[90:91], v[8:9], v[42:43] op_sel:[0,1] op_sel_hi:[1,1]
	v_add_f32_dpp v22, v22, v22 row_half_mirror row_mask:0xf bank_mask:0xf
	v_add_f32_dpp v23, v23, v23 row_half_mirror row_mask:0xf bank_mask:0xf
	v_pk_fma_f32 v[84:85], v[48:49], v[56:57], v[84:85] op_sel:[0,0,0] op_sel_hi:[0,1,1]
	v_pk_fma_f32 v[86:87], v[48:49], v[56:57], v[86:87] op_sel:[1,0,0] op_sel_hi:[1,1,1]
	v_add_f32_dpp v22, v22, v22 row_mirror row_mask:0xf bank_mask:0xf
	v_add_f32_dpp v23, v23, v23 row_mirror row_mask:0xf bank_mask:0xf
	v_pk_fma_f32 v[88:89], v[50:51], v[56:57], v[88:89] op_sel:[0,0,0] op_sel_hi:[0,1,1]
	v_pk_fma_f32 v[90:91], v[50:51], v[56:57], v[90:91] op_sel:[1,0,0] op_sel_hi:[1,1,1]
	v_pk_fma_f32 v[2:3], v[44:45], v[22:23], v[84:85] op_sel:[0,0,0] op_sel_hi:[0,1,1] neg_lo:[1,0,0] neg_hi:[1,0,0]
	v_pk_fma_f32 v[4:5], v[44:45], v[22:23], v[86:87] op_sel:[1,0,0] op_sel_hi:[1,1,1] neg_lo:[1,0,0] neg_hi:[1,0,0]
	v_pk_fma_f32 v[6:7], v[46:47], v[22:23], v[88:89] op_sel:[0,0,0] op_sel_hi:[0,1,1] neg_lo:[1,0,0] neg_hi:[1,0,0]
	v_pk_fma_f32 v[8:9], v[46:47], v[22:23], v[90:91] op_sel:[1,0,0] op_sel_hi:[1,1,1] neg_lo:[1,0,0] neg_hi:[1,0,0]
	s_waitcnt lgkmcnt(0)
	ds_read_b128 v[36:39], v20 offset:1024
	ds_read_b128 v[40:43], v20 offset:9216
	ds_read_b64 v[56:57], v21 offset:41984
	ds_read_b128 v[48:51], v20 offset:25600
	ds_read_b128 v[44:47], v20 offset:17408
	v_pk_mul_f32 v[22:23], v[2:3], v[60:61] op_sel:[0,0] op_sel_hi:[1,0]
	v_pk_mul_f32 v[28:29], v[2:3], v[52:53] op_sel:[0,0] op_sel_hi:[1,0]
	v_pk_fma_f32 v[22:23], v[4:5], v[60:61], v[22:23] op_sel:[0,1,0] op_sel_hi:[1,1,1]
	v_pk_fma_f32 v[28:29], v[4:5], v[52:53], v[28:29] op_sel:[0,1,0] op_sel_hi:[1,1,1]
	v_pk_fma_f32 v[22:23], v[6:7], v[62:63], v[22:23] op_sel:[0,0,0] op_sel_hi:[1,0,1]
	v_pk_fma_f32 v[28:29], v[6:7], v[54:55], v[28:29] op_sel:[0,0,0] op_sel_hi:[1,0,1]
	v_pk_fma_f32 v[22:23], v[8:9], v[62:63], v[22:23] op_sel:[0,1,0] op_sel_hi:[1,1,1]
	v_pk_fma_f32 v[28:29], v[8:9], v[54:55], v[28:29] op_sel:[0,1,0] op_sel_hi:[1,1,1]
	ds_read_b128 v[52:55], v20 offset:33792
	v_add_f32_dpp v24, v24, v24 row_ror:12 row_mask:0xf bank_mask:0x5
	v_add_f32_dpp v25, v25, v25 row_ror:4 row_mask:0xf bank_mask:0xa
	v_add_f32_dpp v22, v22, v22 quad_perm:[1,0,3,2] row_mask:0xf bank_mask:0xf
	v_add_f32_dpp v23, v23, v23 quad_perm:[1,0,3,2] row_mask:0xf bank_mask:0xf
	v_pk_mul_f32 v[84:85], v[2:3], v[64:65] op_sel:[0,0] op_sel_hi:[1,0]
	v_pk_mul_f32 v[86:87], v[4:5], v[64:65] op_sel:[0,1] op_sel_hi:[1,1]
	v_add_f32_dpp v26, v26, v26 row_ror:12 row_mask:0xf bank_mask:0x5
	v_add_f32_dpp v22, v22, v22 quad_perm:[2,3,0,1] row_mask:0xf bank_mask:0xf
	v_add_f32_dpp v23, v23, v23 quad_perm:[2,3,0,1] row_mask:0xf bank_mask:0xf
	v_pk_mul_f32 v[88:89], v[6:7], v[66:67] op_sel:[0,0] op_sel_hi:[1,0]
	v_pk_mul_f32 v[90:91], v[8:9], v[66:67] op_sel:[0,1] op_sel_hi:[1,1]
	v_add_f32_dpp v27, v27, v27 row_ror:4 row_mask:0xf bank_mask:0xa
	v_add_f32_dpp v22, v22, v22 row_half_mirror row_mask:0xf bank_mask:0xf
	v_add_f32_dpp v23, v23, v23 row_half_mirror row_mask:0xf bank_mask:0xf
	v_pk_fma_f32 v[84:85], v[72:73], v[80:81], v[84:85] op_sel:[0,0,0] op_sel_hi:[0,1,1]
	v_pk_fma_f32 v[86:87], v[72:73], v[80:81], v[86:87] op_sel:[1,0,0] op_sel_hi:[1,1,1]
	v_mov_b32_dpp v24, v25 quad_perm:[0,1,2,3] row_mask:0xf bank_mask:0xa
	v_add_f32_dpp v22, v22, v22 row_mirror row_mask:0xf bank_mask:0xf
	v_add_f32_dpp v23, v23, v23 row_mirror row_mask:0xf bank_mask:0xf
	v_pk_fma_f32 v[88:89], v[74:75], v[80:81], v[88:89] op_sel:[0,0,0] op_sel_hi:[0,1,1]
	v_pk_fma_f32 v[90:91], v[74:75], v[80:81], v[90:91] op_sel:[1,0,0] op_sel_hi:[1,1,1]
	v_mov_b32_dpp v26, v27 quad_perm:[0,1,2,3] row_mask:0xf bank_mask:0xa
	v_pk_fma_f32 v[2:3], v[68:69], v[22:23], v[84:85] op_sel:[0,0,0] op_sel_hi:[0,1,1] neg_lo:[1,0,0] neg_hi:[1,0,0]
	v_pk_fma_f32 v[4:5], v[68:69], v[22:23], v[86:87] op_sel:[1,0,0] op_sel_hi:[1,1,1] neg_lo:[1,0,0] neg_hi:[1,0,0]
	v_pk_fma_f32 v[6:7], v[70:71], v[22:23], v[88:89] op_sel:[0,0,0] op_sel_hi:[0,1,1] neg_lo:[1,0,0] neg_hi:[1,0,0]
	v_pk_fma_f32 v[8:9], v[70:71], v[22:23], v[90:91] op_sel:[1,0,0] op_sel_hi:[1,1,1] neg_lo:[1,0,0] neg_hi:[1,0,0]
	s_waitcnt lgkmcnt(0)
	ds_read_b128 v[60:63], v20 offset:1280
	ds_read_b128 v[64:67], v20 offset:9472
	ds_read_b64 v[80:81], v21 offset:42240
	ds_read_b128 v[72:75], v20 offset:25856
	ds_read_b128 v[68:71], v20 offset:17664
	v_pk_mul_f32 v[22:23], v[2:3], v[36:37] op_sel:[0,0] op_sel_hi:[1,0]
	v_pk_mul_f32 v[58:59], v[2:3], v[76:77] op_sel:[0,0] op_sel_hi:[1,0]
	v_pk_fma_f32 v[22:23], v[4:5], v[36:37], v[22:23] op_sel:[0,1,0] op_sel_hi:[1,1,1]
	v_pk_fma_f32 v[58:59], v[4:5], v[76:77], v[58:59] op_sel:[0,1,0] op_sel_hi:[1,1,1]
	v_pk_fma_f32 v[22:23], v[6:7], v[38:39], v[22:23] op_sel:[0,0,0] op_sel_hi:[1,0,1]
	v_pk_fma_f32 v[58:59], v[6:7], v[78:79], v[58:59] op_sel:[0,0,0] op_sel_hi:[1,0,1]
	v_pk_fma_f32 v[22:23], v[8:9], v[38:39], v[22:23] op_sel:[0,1,0] op_sel_hi:[1,1,1]
	v_pk_fma_f32 v[58:59], v[8:9], v[78:79], v[58:59] op_sel:[0,1,0] op_sel_hi:[1,1,1]
	ds_read_b128 v[76:79], v20 offset:34048
	v_add_f32_dpp v24, v24, v24 row_ror:8 row_mask:0xf bank_mask:0x3
	v_add_f32_dpp v26, v26, v26 row_ror:8 row_mask:0xf bank_mask:0xc
	v_add_f32_dpp v22, v22, v22 quad_perm:[1,0,3,2] row_mask:0xf bank_mask:0xf
	v_add_f32_dpp v23, v23, v23 quad_perm:[1,0,3,2] row_mask:0xf bank_mask:0xf
	v_pk_mul_f32 v[84:85], v[2:3], v[40:41] op_sel:[0,0] op_sel_hi:[1,0]
	v_pk_mul_f32 v[86:87], v[4:5], v[40:41] op_sel:[0,1] op_sel_hi:[1,1]
	v_mov_b32_dpp v24, v26 quad_perm:[0,1,2,3] row_mask:0xf bank_mask:0xc
	v_add_f32_dpp v22, v22, v22 quad_perm:[2,3,0,1] row_mask:0xf bank_mask:0xf
	v_add_f32_dpp v23, v23, v23 quad_perm:[2,3,0,1] row_mask:0xf bank_mask:0xf
	v_pk_mul_f32 v[88:89], v[6:7], v[42:43] op_sel:[0,0] op_sel_hi:[1,0]
	v_pk_mul_f32 v[90:91], v[8:9], v[42:43] op_sel:[0,1] op_sel_hi:[1,1]
	v_add_f32_dpp v24, v24, v24 quad_perm:[1,0,3,2] row_mask:0xf bank_mask:0xf
	v_add_f32_dpp v22, v22, v22 row_half_mirror row_mask:0xf bank_mask:0xf
	v_add_f32_dpp v23, v23, v23 row_half_mirror row_mask:0xf bank_mask:0xf
	v_pk_fma_f32 v[84:85], v[48:49], v[56:57], v[84:85] op_sel:[0,0,0] op_sel_hi:[0,1,1]
	v_pk_fma_f32 v[86:87], v[48:49], v[56:57], v[86:87] op_sel:[1,0,0] op_sel_hi:[1,1,1]
	v_add_f32_dpp v24, v24, v24 quad_perm:[2,3,0,1] row_mask:0xf bank_mask:0xf
	v_add_f32_dpp v22, v22, v22 row_mirror row_mask:0xf bank_mask:0xf
	v_add_f32_dpp v23, v23, v23 row_mirror row_mask:0xf bank_mask:0xf
	v_pk_fma_f32 v[88:89], v[50:51], v[56:57], v[88:89] op_sel:[0,0,0] op_sel_hi:[0,1,1]
	v_pk_fma_f32 v[90:91], v[50:51], v[56:57], v[90:91] op_sel:[1,0,0] op_sel_hi:[1,1,1]
	v_cndmask_b32_e64 v30, 0, v24, s[0:1]
	v_pk_fma_f32 v[2:3], v[44:45], v[22:23], v[84:85] op_sel:[0,0,0] op_sel_hi:[0,1,1] neg_lo:[1,0,0] neg_hi:[1,0,0]
	v_pk_fma_f32 v[4:5], v[44:45], v[22:23], v[86:87] op_sel:[1,0,0] op_sel_hi:[1,1,1] neg_lo:[1,0,0] neg_hi:[1,0,0]
	v_pk_fma_f32 v[6:7], v[46:47], v[22:23], v[88:89] op_sel:[0,0,0] op_sel_hi:[0,1,1] neg_lo:[1,0,0] neg_hi:[1,0,0]
	v_pk_fma_f32 v[8:9], v[46:47], v[22:23], v[90:91] op_sel:[1,0,0] op_sel_hi:[1,1,1] neg_lo:[1,0,0] neg_hi:[1,0,0]
	s_waitcnt lgkmcnt(0)
	ds_read_b128 v[36:39], v20 offset:1536
	ds_read_b128 v[40:43], v20 offset:9728
	ds_read_b64 v[56:57], v21 offset:42496
	ds_read_b128 v[48:51], v20 offset:26112
	ds_read_b128 v[44:47], v20 offset:17920
	v_pk_mul_f32 v[22:23], v[2:3], v[60:61] op_sel:[0,0] op_sel_hi:[1,0]
	v_pk_mul_f32 v[24:25], v[2:3], v[52:53] op_sel:[0,0] op_sel_hi:[1,0]
	v_pk_fma_f32 v[22:23], v[4:5], v[60:61], v[22:23] op_sel:[0,1,0] op_sel_hi:[1,1,1]
	v_pk_fma_f32 v[24:25], v[4:5], v[52:53], v[24:25] op_sel:[0,1,0] op_sel_hi:[1,1,1]
	v_pk_fma_f32 v[22:23], v[6:7], v[62:63], v[22:23] op_sel:[0,0,0] op_sel_hi:[1,0,1]
	v_pk_fma_f32 v[24:25], v[6:7], v[54:55], v[24:25] op_sel:[0,0,0] op_sel_hi:[1,0,1]
	v_pk_fma_f32 v[22:23], v[8:9], v[62:63], v[22:23] op_sel:[0,1,0] op_sel_hi:[1,1,1]
	v_pk_fma_f32 v[24:25], v[8:9], v[54:55], v[24:25] op_sel:[0,1,0] op_sel_hi:[1,1,1]
	ds_read_b128 v[52:55], v20 offset:34304
	v_add_f32_dpp v28, v28, v28 row_ror:12 row_mask:0xf bank_mask:0x5
	v_add_f32_dpp v29, v29, v29 row_ror:4 row_mask:0xf bank_mask:0xa
	v_add_f32_dpp v22, v22, v22 quad_perm:[1,0,3,2] row_mask:0xf bank_mask:0xf
	v_add_f32_dpp v23, v23, v23 quad_perm:[1,0,3,2] row_mask:0xf bank_mask:0xf
	v_pk_mul_f32 v[84:85], v[2:3], v[64:65] op_sel:[0,0] op_sel_hi:[1,0]
	v_pk_mul_f32 v[86:87], v[4:5], v[64:65] op_sel:[0,1] op_sel_hi:[1,1]
	v_add_f32_dpp v58, v58, v58 row_ror:12 row_mask:0xf bank_mask:0x5
	v_add_f32_dpp v22, v22, v22 quad_perm:[2,3,0,1] row_mask:0xf bank_mask:0xf
	v_add_f32_dpp v23, v23, v23 quad_perm:[2,3,0,1] row_mask:0xf bank_mask:0xf
	v_pk_mul_f32 v[88:89], v[6:7], v[66:67] op_sel:[0,0] op_sel_hi:[1,0]
	v_pk_mul_f32 v[90:91], v[8:9], v[66:67] op_sel:[0,1] op_sel_hi:[1,1]
	v_add_f32_dpp v59, v59, v59 row_ror:4 row_mask:0xf bank_mask:0xa
	v_add_f32_dpp v22, v22, v22 row_half_mirror row_mask:0xf bank_mask:0xf
	v_add_f32_dpp v23, v23, v23 row_half_mirror row_mask:0xf bank_mask:0xf
	v_pk_fma_f32 v[84:85], v[72:73], v[80:81], v[84:85] op_sel:[0,0,0] op_sel_hi:[0,1,1]
	v_pk_fma_f32 v[86:87], v[72:73], v[80:81], v[86:87] op_sel:[1,0,0] op_sel_hi:[1,1,1]
	v_mov_b32_dpp v28, v29 quad_perm:[0,1,2,3] row_mask:0xf bank_mask:0xa
	v_add_f32_dpp v22, v22, v22 row_mirror row_mask:0xf bank_mask:0xf
	v_add_f32_dpp v23, v23, v23 row_mirror row_mask:0xf bank_mask:0xf
	v_pk_fma_f32 v[88:89], v[74:75], v[80:81], v[88:89] op_sel:[0,0,0] op_sel_hi:[0,1,1]
	v_pk_fma_f32 v[90:91], v[74:75], v[80:81], v[90:91] op_sel:[1,0,0] op_sel_hi:[1,1,1]
	v_mov_b32_dpp v58, v59 quad_perm:[0,1,2,3] row_mask:0xf bank_mask:0xa
	v_pk_fma_f32 v[2:3], v[68:69], v[22:23], v[84:85] op_sel:[0,0,0] op_sel_hi:[0,1,1] neg_lo:[1,0,0] neg_hi:[1,0,0]
	v_pk_fma_f32 v[4:5], v[68:69], v[22:23], v[86:87] op_sel:[1,0,0] op_sel_hi:[1,1,1] neg_lo:[1,0,0] neg_hi:[1,0,0]
	v_pk_fma_f32 v[6:7], v[70:71], v[22:23], v[88:89] op_sel:[0,0,0] op_sel_hi:[0,1,1] neg_lo:[1,0,0] neg_hi:[1,0,0]
	v_pk_fma_f32 v[8:9], v[70:71], v[22:23], v[90:91] op_sel:[1,0,0] op_sel_hi:[1,1,1] neg_lo:[1,0,0] neg_hi:[1,0,0]
	s_waitcnt lgkmcnt(0)
	ds_read_b128 v[60:63], v20 offset:1792
	ds_read_b128 v[64:67], v20 offset:9984
	ds_read_b64 v[80:81], v21 offset:42752
	ds_read_b128 v[72:75], v20 offset:26368
	ds_read_b128 v[68:71], v20 offset:18176
	v_pk_mul_f32 v[22:23], v[2:3], v[36:37] op_sel:[0,0] op_sel_hi:[1,0]
	v_pk_mul_f32 v[26:27], v[2:3], v[76:77] op_sel:[0,0] op_sel_hi:[1,0]
	v_pk_fma_f32 v[22:23], v[4:5], v[36:37], v[22:23] op_sel:[0,1,0] op_sel_hi:[1,1,1]
	v_pk_fma_f32 v[26:27], v[4:5], v[76:77], v[26:27] op_sel:[0,1,0] op_sel_hi:[1,1,1]
	v_pk_fma_f32 v[22:23], v[6:7], v[38:39], v[22:23] op_sel:[0,0,0] op_sel_hi:[1,0,1]
	v_pk_fma_f32 v[26:27], v[6:7], v[78:79], v[26:27] op_sel:[0,0,0] op_sel_hi:[1,0,1]
	v_pk_fma_f32 v[22:23], v[8:9], v[38:39], v[22:23] op_sel:[0,1,0] op_sel_hi:[1,1,1]
	v_pk_fma_f32 v[26:27], v[8:9], v[78:79], v[26:27] op_sel:[0,1,0] op_sel_hi:[1,1,1]
	ds_read_b128 v[76:79], v20 offset:34560
	v_add_f32_dpp v28, v28, v28 row_ror:8 row_mask:0xf bank_mask:0x3
	v_add_f32_dpp v58, v58, v58 row_ror:8 row_mask:0xf bank_mask:0xc
	v_add_f32_dpp v22, v22, v22 quad_perm:[1,0,3,2] row_mask:0xf bank_mask:0xf
	v_add_f32_dpp v23, v23, v23 quad_perm:[1,0,3,2] row_mask:0xf bank_mask:0xf
	v_pk_mul_f32 v[84:85], v[2:3], v[40:41] op_sel:[0,0] op_sel_hi:[1,0]
	v_pk_mul_f32 v[86:87], v[4:5], v[40:41] op_sel:[0,1] op_sel_hi:[1,1]
	v_mov_b32_dpp v28, v58 quad_perm:[0,1,2,3] row_mask:0xf bank_mask:0xc
	v_add_f32_dpp v22, v22, v22 quad_perm:[2,3,0,1] row_mask:0xf bank_mask:0xf
	v_add_f32_dpp v23, v23, v23 quad_perm:[2,3,0,1] row_mask:0xf bank_mask:0xf
	v_pk_mul_f32 v[88:89], v[6:7], v[42:43] op_sel:[0,0] op_sel_hi:[1,0]
	v_pk_mul_f32 v[90:91], v[8:9], v[42:43] op_sel:[0,1] op_sel_hi:[1,1]
	v_add_f32_dpp v28, v28, v28 quad_perm:[1,0,3,2] row_mask:0xf bank_mask:0xf
	v_add_f32_dpp v22, v22, v22 row_half_mirror row_mask:0xf bank_mask:0xf
	v_add_f32_dpp v23, v23, v23 row_half_mirror row_mask:0xf bank_mask:0xf
	v_pk_fma_f32 v[84:85], v[48:49], v[56:57], v[84:85] op_sel:[0,0,0] op_sel_hi:[0,1,1]
	v_pk_fma_f32 v[86:87], v[48:49], v[56:57], v[86:87] op_sel:[1,0,0] op_sel_hi:[1,1,1]
	v_add_f32_dpp v28, v28, v28 quad_perm:[2,3,0,1] row_mask:0xf bank_mask:0xf
	v_add_f32_dpp v22, v22, v22 row_mirror row_mask:0xf bank_mask:0xf
	v_add_f32_dpp v23, v23, v23 row_mirror row_mask:0xf bank_mask:0xf
	v_pk_fma_f32 v[88:89], v[50:51], v[56:57], v[88:89] op_sel:[0,0,0] op_sel_hi:[0,1,1]
	v_pk_fma_f32 v[90:91], v[50:51], v[56:57], v[90:91] op_sel:[1,0,0] op_sel_hi:[1,1,1]
	v_cndmask_b32_e64 v30, v30, v28, s[6:7]
	v_pk_fma_f32 v[2:3], v[44:45], v[22:23], v[84:85] op_sel:[0,0,0] op_sel_hi:[0,1,1] neg_lo:[1,0,0] neg_hi:[1,0,0]
	v_pk_fma_f32 v[4:5], v[44:45], v[22:23], v[86:87] op_sel:[1,0,0] op_sel_hi:[1,1,1] neg_lo:[1,0,0] neg_hi:[1,0,0]
	v_pk_fma_f32 v[6:7], v[46:47], v[22:23], v[88:89] op_sel:[0,0,0] op_sel_hi:[0,1,1] neg_lo:[1,0,0] neg_hi:[1,0,0]
	v_pk_fma_f32 v[8:9], v[46:47], v[22:23], v[90:91] op_sel:[1,0,0] op_sel_hi:[1,1,1] neg_lo:[1,0,0] neg_hi:[1,0,0]
	s_waitcnt lgkmcnt(0)
	ds_read_b128 v[36:39], v20 offset:2048
	ds_read_b128 v[40:43], v20 offset:10240
	ds_read_b64 v[56:57], v21 offset:43008
	ds_read_b128 v[48:51], v20 offset:26624
	ds_read_b128 v[44:47], v20 offset:18432
	v_pk_mul_f32 v[22:23], v[2:3], v[60:61] op_sel:[0,0] op_sel_hi:[1,0]
	v_pk_mul_f32 v[28:29], v[2:3], v[52:53] op_sel:[0,0] op_sel_hi:[1,0]
	v_pk_fma_f32 v[22:23], v[4:5], v[60:61], v[22:23] op_sel:[0,1,0] op_sel_hi:[1,1,1]
	v_pk_fma_f32 v[28:29], v[4:5], v[52:53], v[28:29] op_sel:[0,1,0] op_sel_hi:[1,1,1]
	v_pk_fma_f32 v[22:23], v[6:7], v[62:63], v[22:23] op_sel:[0,0,0] op_sel_hi:[1,0,1]
	v_pk_fma_f32 v[28:29], v[6:7], v[54:55], v[28:29] op_sel:[0,0,0] op_sel_hi:[1,0,1]
	v_pk_fma_f32 v[22:23], v[8:9], v[62:63], v[22:23] op_sel:[0,1,0] op_sel_hi:[1,1,1]
	v_pk_fma_f32 v[28:29], v[8:9], v[54:55], v[28:29] op_sel:[0,1,0] op_sel_hi:[1,1,1]
	ds_read_b128 v[52:55], v20 offset:34816
	v_add_f32_dpp v24, v24, v24 row_ror:12 row_mask:0xf bank_mask:0x5
	v_add_f32_dpp v25, v25, v25 row_ror:4 row_mask:0xf bank_mask:0xa
	v_add_f32_dpp v22, v22, v22 quad_perm:[1,0,3,2] row_mask:0xf bank_mask:0xf
	v_add_f32_dpp v23, v23, v23 quad_perm:[1,0,3,2] row_mask:0xf bank_mask:0xf
	v_pk_mul_f32 v[84:85], v[2:3], v[64:65] op_sel:[0,0] op_sel_hi:[1,0]
	v_pk_mul_f32 v[86:87], v[4:5], v[64:65] op_sel:[0,1] op_sel_hi:[1,1]
	v_add_f32_dpp v26, v26, v26 row_ror:12 row_mask:0xf bank_mask:0x5
	v_add_f32_dpp v22, v22, v22 quad_perm:[2,3,0,1] row_mask:0xf bank_mask:0xf
	v_add_f32_dpp v23, v23, v23 quad_perm:[2,3,0,1] row_mask:0xf bank_mask:0xf
	v_pk_mul_f32 v[88:89], v[6:7], v[66:67] op_sel:[0,0] op_sel_hi:[1,0]
	v_pk_mul_f32 v[90:91], v[8:9], v[66:67] op_sel:[0,1] op_sel_hi:[1,1]
	v_add_f32_dpp v27, v27, v27 row_ror:4 row_mask:0xf bank_mask:0xa
	v_add_f32_dpp v22, v22, v22 row_half_mirror row_mask:0xf bank_mask:0xf
	v_add_f32_dpp v23, v23, v23 row_half_mirror row_mask:0xf bank_mask:0xf
	v_pk_fma_f32 v[84:85], v[72:73], v[80:81], v[84:85] op_sel:[0,0,0] op_sel_hi:[0,1,1]
	v_pk_fma_f32 v[86:87], v[72:73], v[80:81], v[86:87] op_sel:[1,0,0] op_sel_hi:[1,1,1]
	v_mov_b32_dpp v24, v25 quad_perm:[0,1,2,3] row_mask:0xf bank_mask:0xa
	v_add_f32_dpp v22, v22, v22 row_mirror row_mask:0xf bank_mask:0xf
	v_add_f32_dpp v23, v23, v23 row_mirror row_mask:0xf bank_mask:0xf
	v_pk_fma_f32 v[88:89], v[74:75], v[80:81], v[88:89] op_sel:[0,0,0] op_sel_hi:[0,1,1]
	v_pk_fma_f32 v[90:91], v[74:75], v[80:81], v[90:91] op_sel:[1,0,0] op_sel_hi:[1,1,1]
	v_mov_b32_dpp v26, v27 quad_perm:[0,1,2,3] row_mask:0xf bank_mask:0xa
	v_pk_fma_f32 v[2:3], v[68:69], v[22:23], v[84:85] op_sel:[0,0,0] op_sel_hi:[0,1,1] neg_lo:[1,0,0] neg_hi:[1,0,0]
	v_pk_fma_f32 v[4:5], v[68:69], v[22:23], v[86:87] op_sel:[1,0,0] op_sel_hi:[1,1,1] neg_lo:[1,0,0] neg_hi:[1,0,0]
	v_pk_fma_f32 v[6:7], v[70:71], v[22:23], v[88:89] op_sel:[0,0,0] op_sel_hi:[0,1,1] neg_lo:[1,0,0] neg_hi:[1,0,0]
	v_pk_fma_f32 v[8:9], v[70:71], v[22:23], v[90:91] op_sel:[1,0,0] op_sel_hi:[1,1,1] neg_lo:[1,0,0] neg_hi:[1,0,0]
	s_waitcnt lgkmcnt(0)
	ds_read_b128 v[60:63], v20 offset:2304
	ds_read_b128 v[64:67], v20 offset:10496
	ds_read_b64 v[80:81], v21 offset:43264
	ds_read_b128 v[72:75], v20 offset:26880
	ds_read_b128 v[68:71], v20 offset:18688
	v_pk_mul_f32 v[22:23], v[2:3], v[36:37] op_sel:[0,0] op_sel_hi:[1,0]
	v_pk_mul_f32 v[58:59], v[2:3], v[76:77] op_sel:[0,0] op_sel_hi:[1,0]
	v_pk_fma_f32 v[22:23], v[4:5], v[36:37], v[22:23] op_sel:[0,1,0] op_sel_hi:[1,1,1]
	v_pk_fma_f32 v[58:59], v[4:5], v[76:77], v[58:59] op_sel:[0,1,0] op_sel_hi:[1,1,1]
	v_pk_fma_f32 v[22:23], v[6:7], v[38:39], v[22:23] op_sel:[0,0,0] op_sel_hi:[1,0,1]
	v_pk_fma_f32 v[58:59], v[6:7], v[78:79], v[58:59] op_sel:[0,0,0] op_sel_hi:[1,0,1]
	v_pk_fma_f32 v[22:23], v[8:9], v[38:39], v[22:23] op_sel:[0,1,0] op_sel_hi:[1,1,1]
	v_pk_fma_f32 v[58:59], v[8:9], v[78:79], v[58:59] op_sel:[0,1,0] op_sel_hi:[1,1,1]
	ds_read_b128 v[76:79], v20 offset:35072
	v_add_f32_dpp v24, v24, v24 row_ror:8 row_mask:0xf bank_mask:0x3
	v_add_f32_dpp v26, v26, v26 row_ror:8 row_mask:0xf bank_mask:0xc
	v_add_f32_dpp v22, v22, v22 quad_perm:[1,0,3,2] row_mask:0xf bank_mask:0xf
	v_add_f32_dpp v23, v23, v23 quad_perm:[1,0,3,2] row_mask:0xf bank_mask:0xf
	v_pk_mul_f32 v[84:85], v[2:3], v[40:41] op_sel:[0,0] op_sel_hi:[1,0]
	v_pk_mul_f32 v[86:87], v[4:5], v[40:41] op_sel:[0,1] op_sel_hi:[1,1]
	v_mov_b32_dpp v24, v26 quad_perm:[0,1,2,3] row_mask:0xf bank_mask:0xc
	v_add_f32_dpp v22, v22, v22 quad_perm:[2,3,0,1] row_mask:0xf bank_mask:0xf
	v_add_f32_dpp v23, v23, v23 quad_perm:[2,3,0,1] row_mask:0xf bank_mask:0xf
	v_pk_mul_f32 v[88:89], v[6:7], v[42:43] op_sel:[0,0] op_sel_hi:[1,0]
	v_pk_mul_f32 v[90:91], v[8:9], v[42:43] op_sel:[0,1] op_sel_hi:[1,1]
	v_add_f32_dpp v24, v24, v24 quad_perm:[1,0,3,2] row_mask:0xf bank_mask:0xf
	v_add_f32_dpp v22, v22, v22 row_half_mirror row_mask:0xf bank_mask:0xf
	v_add_f32_dpp v23, v23, v23 row_half_mirror row_mask:0xf bank_mask:0xf
	v_pk_fma_f32 v[84:85], v[48:49], v[56:57], v[84:85] op_sel:[0,0,0] op_sel_hi:[0,1,1]
	v_pk_fma_f32 v[86:87], v[48:49], v[56:57], v[86:87] op_sel:[1,0,0] op_sel_hi:[1,1,1]
	v_add_f32_dpp v24, v24, v24 quad_perm:[2,3,0,1] row_mask:0xf bank_mask:0xf
	v_add_f32_dpp v22, v22, v22 row_mirror row_mask:0xf bank_mask:0xf
	v_add_f32_dpp v23, v23, v23 row_mirror row_mask:0xf bank_mask:0xf
	v_pk_fma_f32 v[88:89], v[50:51], v[56:57], v[88:89] op_sel:[0,0,0] op_sel_hi:[0,1,1]
	v_pk_fma_f32 v[90:91], v[50:51], v[56:57], v[90:91] op_sel:[1,0,0] op_sel_hi:[1,1,1]
	v_cndmask_b32_e64 v30, v30, v24, s[8:9]
	v_pk_fma_f32 v[2:3], v[44:45], v[22:23], v[84:85] op_sel:[0,0,0] op_sel_hi:[0,1,1] neg_lo:[1,0,0] neg_hi:[1,0,0]
	v_pk_fma_f32 v[4:5], v[44:45], v[22:23], v[86:87] op_sel:[1,0,0] op_sel_hi:[1,1,1] neg_lo:[1,0,0] neg_hi:[1,0,0]
	v_pk_fma_f32 v[6:7], v[46:47], v[22:23], v[88:89] op_sel:[0,0,0] op_sel_hi:[0,1,1] neg_lo:[1,0,0] neg_hi:[1,0,0]
	v_pk_fma_f32 v[8:9], v[46:47], v[22:23], v[90:91] op_sel:[1,0,0] op_sel_hi:[1,1,1] neg_lo:[1,0,0] neg_hi:[1,0,0]
	s_waitcnt lgkmcnt(0)
	ds_read_b128 v[36:39], v20 offset:2560
	ds_read_b128 v[40:43], v20 offset:10752
	ds_read_b64 v[56:57], v21 offset:43520
	ds_read_b128 v[48:51], v20 offset:27136
	ds_read_b128 v[44:47], v20 offset:18944
	v_pk_mul_f32 v[22:23], v[2:3], v[60:61] op_sel:[0,0] op_sel_hi:[1,0]
	v_pk_mul_f32 v[24:25], v[2:3], v[52:53] op_sel:[0,0] op_sel_hi:[1,0]
	v_pk_fma_f32 v[22:23], v[4:5], v[60:61], v[22:23] op_sel:[0,1,0] op_sel_hi:[1,1,1]
	v_pk_fma_f32 v[24:25], v[4:5], v[52:53], v[24:25] op_sel:[0,1,0] op_sel_hi:[1,1,1]
	v_pk_fma_f32 v[22:23], v[6:7], v[62:63], v[22:23] op_sel:[0,0,0] op_sel_hi:[1,0,1]
	v_pk_fma_f32 v[24:25], v[6:7], v[54:55], v[24:25] op_sel:[0,0,0] op_sel_hi:[1,0,1]
	v_pk_fma_f32 v[22:23], v[8:9], v[62:63], v[22:23] op_sel:[0,1,0] op_sel_hi:[1,1,1]
	v_pk_fma_f32 v[24:25], v[8:9], v[54:55], v[24:25] op_sel:[0,1,0] op_sel_hi:[1,1,1]
	ds_read_b128 v[52:55], v20 offset:35328
	v_add_f32_dpp v28, v28, v28 row_ror:12 row_mask:0xf bank_mask:0x5
	v_add_f32_dpp v29, v29, v29 row_ror:4 row_mask:0xf bank_mask:0xa
	v_add_f32_dpp v22, v22, v22 quad_perm:[1,0,3,2] row_mask:0xf bank_mask:0xf
	v_add_f32_dpp v23, v23, v23 quad_perm:[1,0,3,2] row_mask:0xf bank_mask:0xf
	v_pk_mul_f32 v[84:85], v[2:3], v[64:65] op_sel:[0,0] op_sel_hi:[1,0]
	v_pk_mul_f32 v[86:87], v[4:5], v[64:65] op_sel:[0,1] op_sel_hi:[1,1]
	v_add_f32_dpp v58, v58, v58 row_ror:12 row_mask:0xf bank_mask:0x5
	v_add_f32_dpp v22, v22, v22 quad_perm:[2,3,0,1] row_mask:0xf bank_mask:0xf
	v_add_f32_dpp v23, v23, v23 quad_perm:[2,3,0,1] row_mask:0xf bank_mask:0xf
	v_pk_mul_f32 v[88:89], v[6:7], v[66:67] op_sel:[0,0] op_sel_hi:[1,0]
	v_pk_mul_f32 v[90:91], v[8:9], v[66:67] op_sel:[0,1] op_sel_hi:[1,1]
	v_add_f32_dpp v59, v59, v59 row_ror:4 row_mask:0xf bank_mask:0xa
	v_add_f32_dpp v22, v22, v22 row_half_mirror row_mask:0xf bank_mask:0xf
	v_add_f32_dpp v23, v23, v23 row_half_mirror row_mask:0xf bank_mask:0xf
	v_pk_fma_f32 v[84:85], v[72:73], v[80:81], v[84:85] op_sel:[0,0,0] op_sel_hi:[0,1,1]
	v_pk_fma_f32 v[86:87], v[72:73], v[80:81], v[86:87] op_sel:[1,0,0] op_sel_hi:[1,1,1]
	v_mov_b32_dpp v28, v29 quad_perm:[0,1,2,3] row_mask:0xf bank_mask:0xa
	v_add_f32_dpp v22, v22, v22 row_mirror row_mask:0xf bank_mask:0xf
	v_add_f32_dpp v23, v23, v23 row_mirror row_mask:0xf bank_mask:0xf
	v_pk_fma_f32 v[88:89], v[74:75], v[80:81], v[88:89] op_sel:[0,0,0] op_sel_hi:[0,1,1]
	v_pk_fma_f32 v[90:91], v[74:75], v[80:81], v[90:91] op_sel:[1,0,0] op_sel_hi:[1,1,1]
	v_mov_b32_dpp v58, v59 quad_perm:[0,1,2,3] row_mask:0xf bank_mask:0xa
	v_pk_fma_f32 v[2:3], v[68:69], v[22:23], v[84:85] op_sel:[0,0,0] op_sel_hi:[0,1,1] neg_lo:[1,0,0] neg_hi:[1,0,0]
	v_pk_fma_f32 v[4:5], v[68:69], v[22:23], v[86:87] op_sel:[1,0,0] op_sel_hi:[1,1,1] neg_lo:[1,0,0] neg_hi:[1,0,0]
	v_pk_fma_f32 v[6:7], v[70:71], v[22:23], v[88:89] op_sel:[0,0,0] op_sel_hi:[0,1,1] neg_lo:[1,0,0] neg_hi:[1,0,0]
	v_pk_fma_f32 v[8:9], v[70:71], v[22:23], v[90:91] op_sel:[1,0,0] op_sel_hi:[1,1,1] neg_lo:[1,0,0] neg_hi:[1,0,0]
	s_waitcnt lgkmcnt(0)
	ds_read_b128 v[60:63], v20 offset:2816
	ds_read_b128 v[64:67], v20 offset:11008
	ds_read_b64 v[80:81], v21 offset:43776
	ds_read_b128 v[72:75], v20 offset:27392
	ds_read_b128 v[68:71], v20 offset:19200
	v_pk_mul_f32 v[22:23], v[2:3], v[36:37] op_sel:[0,0] op_sel_hi:[1,0]
	v_pk_mul_f32 v[26:27], v[2:3], v[76:77] op_sel:[0,0] op_sel_hi:[1,0]
	v_pk_fma_f32 v[22:23], v[4:5], v[36:37], v[22:23] op_sel:[0,1,0] op_sel_hi:[1,1,1]
	v_pk_fma_f32 v[26:27], v[4:5], v[76:77], v[26:27] op_sel:[0,1,0] op_sel_hi:[1,1,1]
	v_pk_fma_f32 v[22:23], v[6:7], v[38:39], v[22:23] op_sel:[0,0,0] op_sel_hi:[1,0,1]
	v_pk_fma_f32 v[26:27], v[6:7], v[78:79], v[26:27] op_sel:[0,0,0] op_sel_hi:[1,0,1]
	v_pk_fma_f32 v[22:23], v[8:9], v[38:39], v[22:23] op_sel:[0,1,0] op_sel_hi:[1,1,1]
	v_pk_fma_f32 v[26:27], v[8:9], v[78:79], v[26:27] op_sel:[0,1,0] op_sel_hi:[1,1,1]
	ds_read_b128 v[76:79], v20 offset:35584
	v_add_f32_dpp v28, v28, v28 row_ror:8 row_mask:0xf bank_mask:0x3
	v_add_f32_dpp v58, v58, v58 row_ror:8 row_mask:0xf bank_mask:0xc
	v_add_f32_dpp v22, v22, v22 quad_perm:[1,0,3,2] row_mask:0xf bank_mask:0xf
	v_add_f32_dpp v23, v23, v23 quad_perm:[1,0,3,2] row_mask:0xf bank_mask:0xf
	v_pk_mul_f32 v[84:85], v[2:3], v[40:41] op_sel:[0,0] op_sel_hi:[1,0]
	v_pk_mul_f32 v[86:87], v[4:5], v[40:41] op_sel:[0,1] op_sel_hi:[1,1]
	v_mov_b32_dpp v28, v58 quad_perm:[0,1,2,3] row_mask:0xf bank_mask:0xc
	v_add_f32_dpp v22, v22, v22 quad_perm:[2,3,0,1] row_mask:0xf bank_mask:0xf
	v_add_f32_dpp v23, v23, v23 quad_perm:[2,3,0,1] row_mask:0xf bank_mask:0xf
	v_pk_mul_f32 v[88:89], v[6:7], v[42:43] op_sel:[0,0] op_sel_hi:[1,0]
	v_pk_mul_f32 v[90:91], v[8:9], v[42:43] op_sel:[0,1] op_sel_hi:[1,1]
	v_add_f32_dpp v28, v28, v28 quad_perm:[1,0,3,2] row_mask:0xf bank_mask:0xf
	v_add_f32_dpp v22, v22, v22 row_half_mirror row_mask:0xf bank_mask:0xf
	v_add_f32_dpp v23, v23, v23 row_half_mirror row_mask:0xf bank_mask:0xf
	v_pk_fma_f32 v[84:85], v[48:49], v[56:57], v[84:85] op_sel:[0,0,0] op_sel_hi:[0,1,1]
	v_pk_fma_f32 v[86:87], v[48:49], v[56:57], v[86:87] op_sel:[1,0,0] op_sel_hi:[1,1,1]
	v_add_f32_dpp v28, v28, v28 quad_perm:[2,3,0,1] row_mask:0xf bank_mask:0xf
	v_add_f32_dpp v22, v22, v22 row_mirror row_mask:0xf bank_mask:0xf
	v_add_f32_dpp v23, v23, v23 row_mirror row_mask:0xf bank_mask:0xf
	v_pk_fma_f32 v[88:89], v[50:51], v[56:57], v[88:89] op_sel:[0,0,0] op_sel_hi:[0,1,1]
	v_pk_fma_f32 v[90:91], v[50:51], v[56:57], v[90:91] op_sel:[1,0,0] op_sel_hi:[1,1,1]
	v_cndmask_b32_e64 v30, v30, v28, s[10:11]
	v_pk_fma_f32 v[2:3], v[44:45], v[22:23], v[84:85] op_sel:[0,0,0] op_sel_hi:[0,1,1] neg_lo:[1,0,0] neg_hi:[1,0,0]
	v_pk_fma_f32 v[4:5], v[44:45], v[22:23], v[86:87] op_sel:[1,0,0] op_sel_hi:[1,1,1] neg_lo:[1,0,0] neg_hi:[1,0,0]
	v_pk_fma_f32 v[6:7], v[46:47], v[22:23], v[88:89] op_sel:[0,0,0] op_sel_hi:[0,1,1] neg_lo:[1,0,0] neg_hi:[1,0,0]
	v_pk_fma_f32 v[8:9], v[46:47], v[22:23], v[90:91] op_sel:[1,0,0] op_sel_hi:[1,1,1] neg_lo:[1,0,0] neg_hi:[1,0,0]
	s_waitcnt lgkmcnt(0)
	ds_read_b128 v[36:39], v20 offset:3072
	ds_read_b128 v[40:43], v20 offset:11264
	ds_read_b64 v[56:57], v21 offset:44032
	ds_read_b128 v[48:51], v20 offset:27648
	ds_read_b128 v[44:47], v20 offset:19456
	v_pk_mul_f32 v[22:23], v[2:3], v[60:61] op_sel:[0,0] op_sel_hi:[1,0]
	v_pk_mul_f32 v[28:29], v[2:3], v[52:53] op_sel:[0,0] op_sel_hi:[1,0]
	v_pk_fma_f32 v[22:23], v[4:5], v[60:61], v[22:23] op_sel:[0,1,0] op_sel_hi:[1,1,1]
	v_pk_fma_f32 v[28:29], v[4:5], v[52:53], v[28:29] op_sel:[0,1,0] op_sel_hi:[1,1,1]
	v_pk_fma_f32 v[22:23], v[6:7], v[62:63], v[22:23] op_sel:[0,0,0] op_sel_hi:[1,0,1]
	v_pk_fma_f32 v[28:29], v[6:7], v[54:55], v[28:29] op_sel:[0,0,0] op_sel_hi:[1,0,1]
	v_pk_fma_f32 v[22:23], v[8:9], v[62:63], v[22:23] op_sel:[0,1,0] op_sel_hi:[1,1,1]
	v_pk_fma_f32 v[28:29], v[8:9], v[54:55], v[28:29] op_sel:[0,1,0] op_sel_hi:[1,1,1]
	ds_read_b128 v[52:55], v20 offset:35840
	v_add_f32_dpp v24, v24, v24 row_ror:12 row_mask:0xf bank_mask:0x5
	v_add_f32_dpp v25, v25, v25 row_ror:4 row_mask:0xf bank_mask:0xa
	v_add_f32_dpp v22, v22, v22 quad_perm:[1,0,3,2] row_mask:0xf bank_mask:0xf
	v_add_f32_dpp v23, v23, v23 quad_perm:[1,0,3,2] row_mask:0xf bank_mask:0xf
	v_pk_mul_f32 v[84:85], v[2:3], v[64:65] op_sel:[0,0] op_sel_hi:[1,0]
	v_pk_mul_f32 v[86:87], v[4:5], v[64:65] op_sel:[0,1] op_sel_hi:[1,1]
	v_add_f32_dpp v26, v26, v26 row_ror:12 row_mask:0xf bank_mask:0x5
	v_add_f32_dpp v22, v22, v22 quad_perm:[2,3,0,1] row_mask:0xf bank_mask:0xf
	v_add_f32_dpp v23, v23, v23 quad_perm:[2,3,0,1] row_mask:0xf bank_mask:0xf
	v_pk_mul_f32 v[88:89], v[6:7], v[66:67] op_sel:[0,0] op_sel_hi:[1,0]
	v_pk_mul_f32 v[90:91], v[8:9], v[66:67] op_sel:[0,1] op_sel_hi:[1,1]
	v_add_f32_dpp v27, v27, v27 row_ror:4 row_mask:0xf bank_mask:0xa
	v_add_f32_dpp v22, v22, v22 row_half_mirror row_mask:0xf bank_mask:0xf
	v_add_f32_dpp v23, v23, v23 row_half_mirror row_mask:0xf bank_mask:0xf
	v_pk_fma_f32 v[84:85], v[72:73], v[80:81], v[84:85] op_sel:[0,0,0] op_sel_hi:[0,1,1]
	v_pk_fma_f32 v[86:87], v[72:73], v[80:81], v[86:87] op_sel:[1,0,0] op_sel_hi:[1,1,1]
	v_mov_b32_dpp v24, v25 quad_perm:[0,1,2,3] row_mask:0xf bank_mask:0xa
	v_add_f32_dpp v22, v22, v22 row_mirror row_mask:0xf bank_mask:0xf
	v_add_f32_dpp v23, v23, v23 row_mirror row_mask:0xf bank_mask:0xf
	v_pk_fma_f32 v[88:89], v[74:75], v[80:81], v[88:89] op_sel:[0,0,0] op_sel_hi:[0,1,1]
	v_pk_fma_f32 v[90:91], v[74:75], v[80:81], v[90:91] op_sel:[1,0,0] op_sel_hi:[1,1,1]
	v_mov_b32_dpp v26, v27 quad_perm:[0,1,2,3] row_mask:0xf bank_mask:0xa
	v_pk_fma_f32 v[2:3], v[68:69], v[22:23], v[84:85] op_sel:[0,0,0] op_sel_hi:[0,1,1] neg_lo:[1,0,0] neg_hi:[1,0,0]
	v_pk_fma_f32 v[4:5], v[68:69], v[22:23], v[86:87] op_sel:[1,0,0] op_sel_hi:[1,1,1] neg_lo:[1,0,0] neg_hi:[1,0,0]
	v_pk_fma_f32 v[6:7], v[70:71], v[22:23], v[88:89] op_sel:[0,0,0] op_sel_hi:[0,1,1] neg_lo:[1,0,0] neg_hi:[1,0,0]
	v_pk_fma_f32 v[8:9], v[70:71], v[22:23], v[90:91] op_sel:[1,0,0] op_sel_hi:[1,1,1] neg_lo:[1,0,0] neg_hi:[1,0,0]
	s_waitcnt lgkmcnt(0)
	ds_read_b128 v[60:63], v20 offset:3328
	ds_read_b128 v[64:67], v20 offset:11520
	ds_read_b64 v[80:81], v21 offset:44288
	ds_read_b128 v[72:75], v20 offset:27904
	ds_read_b128 v[68:71], v20 offset:19712
	v_pk_mul_f32 v[22:23], v[2:3], v[36:37] op_sel:[0,0] op_sel_hi:[1,0]
	v_pk_mul_f32 v[58:59], v[2:3], v[76:77] op_sel:[0,0] op_sel_hi:[1,0]
	v_pk_fma_f32 v[22:23], v[4:5], v[36:37], v[22:23] op_sel:[0,1,0] op_sel_hi:[1,1,1]
	v_pk_fma_f32 v[58:59], v[4:5], v[76:77], v[58:59] op_sel:[0,1,0] op_sel_hi:[1,1,1]
	v_pk_fma_f32 v[22:23], v[6:7], v[38:39], v[22:23] op_sel:[0,0,0] op_sel_hi:[1,0,1]
	v_pk_fma_f32 v[58:59], v[6:7], v[78:79], v[58:59] op_sel:[0,0,0] op_sel_hi:[1,0,1]
	v_pk_fma_f32 v[22:23], v[8:9], v[38:39], v[22:23] op_sel:[0,1,0] op_sel_hi:[1,1,1]
	v_pk_fma_f32 v[58:59], v[8:9], v[78:79], v[58:59] op_sel:[0,1,0] op_sel_hi:[1,1,1]
	ds_read_b128 v[76:79], v20 offset:36096
	v_add_f32_dpp v24, v24, v24 row_ror:8 row_mask:0xf bank_mask:0x3
	v_add_f32_dpp v26, v26, v26 row_ror:8 row_mask:0xf bank_mask:0xc
	v_add_f32_dpp v22, v22, v22 quad_perm:[1,0,3,2] row_mask:0xf bank_mask:0xf
	v_add_f32_dpp v23, v23, v23 quad_perm:[1,0,3,2] row_mask:0xf bank_mask:0xf
	v_pk_mul_f32 v[84:85], v[2:3], v[40:41] op_sel:[0,0] op_sel_hi:[1,0]
	v_pk_mul_f32 v[86:87], v[4:5], v[40:41] op_sel:[0,1] op_sel_hi:[1,1]
	v_mov_b32_dpp v24, v26 quad_perm:[0,1,2,3] row_mask:0xf bank_mask:0xc
	v_add_f32_dpp v22, v22, v22 quad_perm:[2,3,0,1] row_mask:0xf bank_mask:0xf
	v_add_f32_dpp v23, v23, v23 quad_perm:[2,3,0,1] row_mask:0xf bank_mask:0xf
	v_pk_mul_f32 v[88:89], v[6:7], v[42:43] op_sel:[0,0] op_sel_hi:[1,0]
	v_pk_mul_f32 v[90:91], v[8:9], v[42:43] op_sel:[0,1] op_sel_hi:[1,1]
	v_add_f32_dpp v24, v24, v24 quad_perm:[1,0,3,2] row_mask:0xf bank_mask:0xf
	v_add_f32_dpp v22, v22, v22 row_half_mirror row_mask:0xf bank_mask:0xf
	v_add_f32_dpp v23, v23, v23 row_half_mirror row_mask:0xf bank_mask:0xf
	v_pk_fma_f32 v[84:85], v[48:49], v[56:57], v[84:85] op_sel:[0,0,0] op_sel_hi:[0,1,1]
	v_pk_fma_f32 v[86:87], v[48:49], v[56:57], v[86:87] op_sel:[1,0,0] op_sel_hi:[1,1,1]
	v_add_f32_dpp v24, v24, v24 quad_perm:[2,3,0,1] row_mask:0xf bank_mask:0xf
	v_add_f32_dpp v22, v22, v22 row_mirror row_mask:0xf bank_mask:0xf
	v_add_f32_dpp v23, v23, v23 row_mirror row_mask:0xf bank_mask:0xf
	v_pk_fma_f32 v[88:89], v[50:51], v[56:57], v[88:89] op_sel:[0,0,0] op_sel_hi:[0,1,1]
	v_pk_fma_f32 v[90:91], v[50:51], v[56:57], v[90:91] op_sel:[1,0,0] op_sel_hi:[1,1,1]
	v_cndmask_b32_e64 v31, 0, v24, s[0:1]
	v_pk_fma_f32 v[2:3], v[44:45], v[22:23], v[84:85] op_sel:[0,0,0] op_sel_hi:[0,1,1] neg_lo:[1,0,0] neg_hi:[1,0,0]
	v_pk_fma_f32 v[4:5], v[44:45], v[22:23], v[86:87] op_sel:[1,0,0] op_sel_hi:[1,1,1] neg_lo:[1,0,0] neg_hi:[1,0,0]
	v_pk_fma_f32 v[6:7], v[46:47], v[22:23], v[88:89] op_sel:[0,0,0] op_sel_hi:[0,1,1] neg_lo:[1,0,0] neg_hi:[1,0,0]
	v_pk_fma_f32 v[8:9], v[46:47], v[22:23], v[90:91] op_sel:[1,0,0] op_sel_hi:[1,1,1] neg_lo:[1,0,0] neg_hi:[1,0,0]
	s_waitcnt lgkmcnt(0)
	ds_read_b128 v[36:39], v20 offset:3584
	ds_read_b128 v[40:43], v20 offset:11776
	ds_read_b64 v[56:57], v21 offset:44544
	ds_read_b128 v[48:51], v20 offset:28160
	ds_read_b128 v[44:47], v20 offset:19968
	v_pk_mul_f32 v[22:23], v[2:3], v[60:61] op_sel:[0,0] op_sel_hi:[1,0]
	v_pk_mul_f32 v[24:25], v[2:3], v[52:53] op_sel:[0,0] op_sel_hi:[1,0]
	v_pk_fma_f32 v[22:23], v[4:5], v[60:61], v[22:23] op_sel:[0,1,0] op_sel_hi:[1,1,1]
	v_pk_fma_f32 v[24:25], v[4:5], v[52:53], v[24:25] op_sel:[0,1,0] op_sel_hi:[1,1,1]
	v_pk_fma_f32 v[22:23], v[6:7], v[62:63], v[22:23] op_sel:[0,0,0] op_sel_hi:[1,0,1]
	v_pk_fma_f32 v[24:25], v[6:7], v[54:55], v[24:25] op_sel:[0,0,0] op_sel_hi:[1,0,1]
	v_pk_fma_f32 v[22:23], v[8:9], v[62:63], v[22:23] op_sel:[0,1,0] op_sel_hi:[1,1,1]
	v_pk_fma_f32 v[24:25], v[8:9], v[54:55], v[24:25] op_sel:[0,1,0] op_sel_hi:[1,1,1]
	ds_read_b128 v[52:55], v20 offset:36352
	v_add_f32_dpp v28, v28, v28 row_ror:12 row_mask:0xf bank_mask:0x5
	v_add_f32_dpp v29, v29, v29 row_ror:4 row_mask:0xf bank_mask:0xa
	v_add_f32_dpp v22, v22, v22 quad_perm:[1,0,3,2] row_mask:0xf bank_mask:0xf
	v_add_f32_dpp v23, v23, v23 quad_perm:[1,0,3,2] row_mask:0xf bank_mask:0xf
	v_pk_mul_f32 v[84:85], v[2:3], v[64:65] op_sel:[0,0] op_sel_hi:[1,0]
	v_pk_mul_f32 v[86:87], v[4:5], v[64:65] op_sel:[0,1] op_sel_hi:[1,1]
	v_add_f32_dpp v58, v58, v58 row_ror:12 row_mask:0xf bank_mask:0x5
	v_add_f32_dpp v22, v22, v22 quad_perm:[2,3,0,1] row_mask:0xf bank_mask:0xf
	v_add_f32_dpp v23, v23, v23 quad_perm:[2,3,0,1] row_mask:0xf bank_mask:0xf
	v_pk_mul_f32 v[88:89], v[6:7], v[66:67] op_sel:[0,0] op_sel_hi:[1,0]
	v_pk_mul_f32 v[90:91], v[8:9], v[66:67] op_sel:[0,1] op_sel_hi:[1,1]
	v_add_f32_dpp v59, v59, v59 row_ror:4 row_mask:0xf bank_mask:0xa
	v_add_f32_dpp v22, v22, v22 row_half_mirror row_mask:0xf bank_mask:0xf
	v_add_f32_dpp v23, v23, v23 row_half_mirror row_mask:0xf bank_mask:0xf
	v_pk_fma_f32 v[84:85], v[72:73], v[80:81], v[84:85] op_sel:[0,0,0] op_sel_hi:[0,1,1]
	v_pk_fma_f32 v[86:87], v[72:73], v[80:81], v[86:87] op_sel:[1,0,0] op_sel_hi:[1,1,1]
	v_mov_b32_dpp v28, v29 quad_perm:[0,1,2,3] row_mask:0xf bank_mask:0xa
	v_add_f32_dpp v22, v22, v22 row_mirror row_mask:0xf bank_mask:0xf
	v_add_f32_dpp v23, v23, v23 row_mirror row_mask:0xf bank_mask:0xf
	v_pk_fma_f32 v[88:89], v[74:75], v[80:81], v[88:89] op_sel:[0,0,0] op_sel_hi:[0,1,1]
	v_pk_fma_f32 v[90:91], v[74:75], v[80:81], v[90:91] op_sel:[1,0,0] op_sel_hi:[1,1,1]
	v_mov_b32_dpp v58, v59 quad_perm:[0,1,2,3] row_mask:0xf bank_mask:0xa
	v_pk_fma_f32 v[2:3], v[68:69], v[22:23], v[84:85] op_sel:[0,0,0] op_sel_hi:[0,1,1] neg_lo:[1,0,0] neg_hi:[1,0,0]
	v_pk_fma_f32 v[4:5], v[68:69], v[22:23], v[86:87] op_sel:[1,0,0] op_sel_hi:[1,1,1] neg_lo:[1,0,0] neg_hi:[1,0,0]
	v_pk_fma_f32 v[6:7], v[70:71], v[22:23], v[88:89] op_sel:[0,0,0] op_sel_hi:[0,1,1] neg_lo:[1,0,0] neg_hi:[1,0,0]
	v_pk_fma_f32 v[8:9], v[70:71], v[22:23], v[90:91] op_sel:[1,0,0] op_sel_hi:[1,1,1] neg_lo:[1,0,0] neg_hi:[1,0,0]
	s_waitcnt lgkmcnt(0)
	ds_read_b128 v[60:63], v20 offset:3840
	ds_read_b128 v[64:67], v20 offset:12032
	ds_read_b64 v[80:81], v21 offset:44800
	ds_read_b128 v[72:75], v20 offset:28416
	ds_read_b128 v[68:71], v20 offset:20224
	v_pk_mul_f32 v[22:23], v[2:3], v[36:37] op_sel:[0,0] op_sel_hi:[1,0]
	v_pk_mul_f32 v[26:27], v[2:3], v[76:77] op_sel:[0,0] op_sel_hi:[1,0]
	v_pk_fma_f32 v[22:23], v[4:5], v[36:37], v[22:23] op_sel:[0,1,0] op_sel_hi:[1,1,1]
	v_pk_fma_f32 v[26:27], v[4:5], v[76:77], v[26:27] op_sel:[0,1,0] op_sel_hi:[1,1,1]
	v_pk_fma_f32 v[22:23], v[6:7], v[38:39], v[22:23] op_sel:[0,0,0] op_sel_hi:[1,0,1]
	v_pk_fma_f32 v[26:27], v[6:7], v[78:79], v[26:27] op_sel:[0,0,0] op_sel_hi:[1,0,1]
	v_pk_fma_f32 v[22:23], v[8:9], v[38:39], v[22:23] op_sel:[0,1,0] op_sel_hi:[1,1,1]
	v_pk_fma_f32 v[26:27], v[8:9], v[78:79], v[26:27] op_sel:[0,1,0] op_sel_hi:[1,1,1]
	ds_read_b128 v[76:79], v20 offset:36608
	v_add_f32_dpp v28, v28, v28 row_ror:8 row_mask:0xf bank_mask:0x3
	v_add_f32_dpp v58, v58, v58 row_ror:8 row_mask:0xf bank_mask:0xc
	v_add_f32_dpp v22, v22, v22 quad_perm:[1,0,3,2] row_mask:0xf bank_mask:0xf
	v_add_f32_dpp v23, v23, v23 quad_perm:[1,0,3,2] row_mask:0xf bank_mask:0xf
	v_pk_mul_f32 v[84:85], v[2:3], v[40:41] op_sel:[0,0] op_sel_hi:[1,0]
	v_pk_mul_f32 v[86:87], v[4:5], v[40:41] op_sel:[0,1] op_sel_hi:[1,1]
	v_mov_b32_dpp v28, v58 quad_perm:[0,1,2,3] row_mask:0xf bank_mask:0xc
	v_add_f32_dpp v22, v22, v22 quad_perm:[2,3,0,1] row_mask:0xf bank_mask:0xf
	v_add_f32_dpp v23, v23, v23 quad_perm:[2,3,0,1] row_mask:0xf bank_mask:0xf
	v_pk_mul_f32 v[88:89], v[6:7], v[42:43] op_sel:[0,0] op_sel_hi:[1,0]
	v_pk_mul_f32 v[90:91], v[8:9], v[42:43] op_sel:[0,1] op_sel_hi:[1,1]
	v_add_f32_dpp v28, v28, v28 quad_perm:[1,0,3,2] row_mask:0xf bank_mask:0xf
	v_add_f32_dpp v22, v22, v22 row_half_mirror row_mask:0xf bank_mask:0xf
	v_add_f32_dpp v23, v23, v23 row_half_mirror row_mask:0xf bank_mask:0xf
	v_pk_fma_f32 v[84:85], v[48:49], v[56:57], v[84:85] op_sel:[0,0,0] op_sel_hi:[0,1,1]
	v_pk_fma_f32 v[86:87], v[48:49], v[56:57], v[86:87] op_sel:[1,0,0] op_sel_hi:[1,1,1]
	v_add_f32_dpp v28, v28, v28 quad_perm:[2,3,0,1] row_mask:0xf bank_mask:0xf
	v_add_f32_dpp v22, v22, v22 row_mirror row_mask:0xf bank_mask:0xf
	v_add_f32_dpp v23, v23, v23 row_mirror row_mask:0xf bank_mask:0xf
	v_pk_fma_f32 v[88:89], v[50:51], v[56:57], v[88:89] op_sel:[0,0,0] op_sel_hi:[0,1,1]
	v_pk_fma_f32 v[90:91], v[50:51], v[56:57], v[90:91] op_sel:[1,0,0] op_sel_hi:[1,1,1]
	v_cndmask_b32_e64 v31, v31, v28, s[6:7]
	v_pk_fma_f32 v[2:3], v[44:45], v[22:23], v[84:85] op_sel:[0,0,0] op_sel_hi:[0,1,1] neg_lo:[1,0,0] neg_hi:[1,0,0]
	v_pk_fma_f32 v[4:5], v[44:45], v[22:23], v[86:87] op_sel:[1,0,0] op_sel_hi:[1,1,1] neg_lo:[1,0,0] neg_hi:[1,0,0]
	v_pk_fma_f32 v[6:7], v[46:47], v[22:23], v[88:89] op_sel:[0,0,0] op_sel_hi:[0,1,1] neg_lo:[1,0,0] neg_hi:[1,0,0]
	v_pk_fma_f32 v[8:9], v[46:47], v[22:23], v[90:91] op_sel:[1,0,0] op_sel_hi:[1,1,1] neg_lo:[1,0,0] neg_hi:[1,0,0]
	s_waitcnt lgkmcnt(0)
	ds_read_b128 v[36:39], v20 offset:4096
	ds_read_b128 v[40:43], v20 offset:12288
	ds_read_b64 v[56:57], v21 offset:45056
	ds_read_b128 v[48:51], v20 offset:28672
	ds_read_b128 v[44:47], v20 offset:20480
	v_pk_mul_f32 v[22:23], v[2:3], v[60:61] op_sel:[0,0] op_sel_hi:[1,0]
	v_pk_mul_f32 v[28:29], v[2:3], v[52:53] op_sel:[0,0] op_sel_hi:[1,0]
	v_pk_fma_f32 v[22:23], v[4:5], v[60:61], v[22:23] op_sel:[0,1,0] op_sel_hi:[1,1,1]
	v_pk_fma_f32 v[28:29], v[4:5], v[52:53], v[28:29] op_sel:[0,1,0] op_sel_hi:[1,1,1]
	v_pk_fma_f32 v[22:23], v[6:7], v[62:63], v[22:23] op_sel:[0,0,0] op_sel_hi:[1,0,1]
	v_pk_fma_f32 v[28:29], v[6:7], v[54:55], v[28:29] op_sel:[0,0,0] op_sel_hi:[1,0,1]
	v_pk_fma_f32 v[22:23], v[8:9], v[62:63], v[22:23] op_sel:[0,1,0] op_sel_hi:[1,1,1]
	v_pk_fma_f32 v[28:29], v[8:9], v[54:55], v[28:29] op_sel:[0,1,0] op_sel_hi:[1,1,1]
	ds_read_b128 v[52:55], v20 offset:36864
	v_add_f32_dpp v24, v24, v24 row_ror:12 row_mask:0xf bank_mask:0x5
	v_add_f32_dpp v25, v25, v25 row_ror:4 row_mask:0xf bank_mask:0xa
	v_add_f32_dpp v22, v22, v22 quad_perm:[1,0,3,2] row_mask:0xf bank_mask:0xf
	v_add_f32_dpp v23, v23, v23 quad_perm:[1,0,3,2] row_mask:0xf bank_mask:0xf
	v_pk_mul_f32 v[84:85], v[2:3], v[64:65] op_sel:[0,0] op_sel_hi:[1,0]
	v_pk_mul_f32 v[86:87], v[4:5], v[64:65] op_sel:[0,1] op_sel_hi:[1,1]
	v_add_f32_dpp v26, v26, v26 row_ror:12 row_mask:0xf bank_mask:0x5
	v_add_f32_dpp v22, v22, v22 quad_perm:[2,3,0,1] row_mask:0xf bank_mask:0xf
	v_add_f32_dpp v23, v23, v23 quad_perm:[2,3,0,1] row_mask:0xf bank_mask:0xf
	v_pk_mul_f32 v[88:89], v[6:7], v[66:67] op_sel:[0,0] op_sel_hi:[1,0]
	v_pk_mul_f32 v[90:91], v[8:9], v[66:67] op_sel:[0,1] op_sel_hi:[1,1]
	v_add_f32_dpp v27, v27, v27 row_ror:4 row_mask:0xf bank_mask:0xa
	v_add_f32_dpp v22, v22, v22 row_half_mirror row_mask:0xf bank_mask:0xf
	v_add_f32_dpp v23, v23, v23 row_half_mirror row_mask:0xf bank_mask:0xf
	v_pk_fma_f32 v[84:85], v[72:73], v[80:81], v[84:85] op_sel:[0,0,0] op_sel_hi:[0,1,1]
	v_pk_fma_f32 v[86:87], v[72:73], v[80:81], v[86:87] op_sel:[1,0,0] op_sel_hi:[1,1,1]
	v_mov_b32_dpp v24, v25 quad_perm:[0,1,2,3] row_mask:0xf bank_mask:0xa
	v_add_f32_dpp v22, v22, v22 row_mirror row_mask:0xf bank_mask:0xf
	v_add_f32_dpp v23, v23, v23 row_mirror row_mask:0xf bank_mask:0xf
	v_pk_fma_f32 v[88:89], v[74:75], v[80:81], v[88:89] op_sel:[0,0,0] op_sel_hi:[0,1,1]
	v_pk_fma_f32 v[90:91], v[74:75], v[80:81], v[90:91] op_sel:[1,0,0] op_sel_hi:[1,1,1]
	v_mov_b32_dpp v26, v27 quad_perm:[0,1,2,3] row_mask:0xf bank_mask:0xa
	v_pk_fma_f32 v[2:3], v[68:69], v[22:23], v[84:85] op_sel:[0,0,0] op_sel_hi:[0,1,1] neg_lo:[1,0,0] neg_hi:[1,0,0]
	v_pk_fma_f32 v[4:5], v[68:69], v[22:23], v[86:87] op_sel:[1,0,0] op_sel_hi:[1,1,1] neg_lo:[1,0,0] neg_hi:[1,0,0]
	v_pk_fma_f32 v[6:7], v[70:71], v[22:23], v[88:89] op_sel:[0,0,0] op_sel_hi:[0,1,1] neg_lo:[1,0,0] neg_hi:[1,0,0]
	v_pk_fma_f32 v[8:9], v[70:71], v[22:23], v[90:91] op_sel:[1,0,0] op_sel_hi:[1,1,1] neg_lo:[1,0,0] neg_hi:[1,0,0]
	s_waitcnt lgkmcnt(0)
	ds_read_b128 v[60:63], v20 offset:4352
	ds_read_b128 v[64:67], v20 offset:12544
	ds_read_b64 v[80:81], v21 offset:45312
	ds_read_b128 v[72:75], v20 offset:28928
	ds_read_b128 v[68:71], v20 offset:20736
	v_pk_mul_f32 v[22:23], v[2:3], v[36:37] op_sel:[0,0] op_sel_hi:[1,0]
	v_pk_mul_f32 v[58:59], v[2:3], v[76:77] op_sel:[0,0] op_sel_hi:[1,0]
	v_pk_fma_f32 v[22:23], v[4:5], v[36:37], v[22:23] op_sel:[0,1,0] op_sel_hi:[1,1,1]
	v_pk_fma_f32 v[58:59], v[4:5], v[76:77], v[58:59] op_sel:[0,1,0] op_sel_hi:[1,1,1]
	v_pk_fma_f32 v[22:23], v[6:7], v[38:39], v[22:23] op_sel:[0,0,0] op_sel_hi:[1,0,1]
	v_pk_fma_f32 v[58:59], v[6:7], v[78:79], v[58:59] op_sel:[0,0,0] op_sel_hi:[1,0,1]
	v_pk_fma_f32 v[22:23], v[8:9], v[38:39], v[22:23] op_sel:[0,1,0] op_sel_hi:[1,1,1]
	v_pk_fma_f32 v[58:59], v[8:9], v[78:79], v[58:59] op_sel:[0,1,0] op_sel_hi:[1,1,1]
	ds_read_b128 v[76:79], v20 offset:37120
	v_add_f32_dpp v24, v24, v24 row_ror:8 row_mask:0xf bank_mask:0x3
	v_add_f32_dpp v26, v26, v26 row_ror:8 row_mask:0xf bank_mask:0xc
	v_add_f32_dpp v22, v22, v22 quad_perm:[1,0,3,2] row_mask:0xf bank_mask:0xf
	v_add_f32_dpp v23, v23, v23 quad_perm:[1,0,3,2] row_mask:0xf bank_mask:0xf
	v_pk_mul_f32 v[84:85], v[2:3], v[40:41] op_sel:[0,0] op_sel_hi:[1,0]
	v_pk_mul_f32 v[86:87], v[4:5], v[40:41] op_sel:[0,1] op_sel_hi:[1,1]
	v_mov_b32_dpp v24, v26 quad_perm:[0,1,2,3] row_mask:0xf bank_mask:0xc
	v_add_f32_dpp v22, v22, v22 quad_perm:[2,3,0,1] row_mask:0xf bank_mask:0xf
	v_add_f32_dpp v23, v23, v23 quad_perm:[2,3,0,1] row_mask:0xf bank_mask:0xf
	v_pk_mul_f32 v[88:89], v[6:7], v[42:43] op_sel:[0,0] op_sel_hi:[1,0]
	v_pk_mul_f32 v[90:91], v[8:9], v[42:43] op_sel:[0,1] op_sel_hi:[1,1]
	v_add_f32_dpp v24, v24, v24 quad_perm:[1,0,3,2] row_mask:0xf bank_mask:0xf
	v_add_f32_dpp v22, v22, v22 row_half_mirror row_mask:0xf bank_mask:0xf
	v_add_f32_dpp v23, v23, v23 row_half_mirror row_mask:0xf bank_mask:0xf
	v_pk_fma_f32 v[84:85], v[48:49], v[56:57], v[84:85] op_sel:[0,0,0] op_sel_hi:[0,1,1]
	v_pk_fma_f32 v[86:87], v[48:49], v[56:57], v[86:87] op_sel:[1,0,0] op_sel_hi:[1,1,1]
	v_add_f32_dpp v24, v24, v24 quad_perm:[2,3,0,1] row_mask:0xf bank_mask:0xf
	v_add_f32_dpp v22, v22, v22 row_mirror row_mask:0xf bank_mask:0xf
	v_add_f32_dpp v23, v23, v23 row_mirror row_mask:0xf bank_mask:0xf
	v_pk_fma_f32 v[88:89], v[50:51], v[56:57], v[88:89] op_sel:[0,0,0] op_sel_hi:[0,1,1]
	v_pk_fma_f32 v[90:91], v[50:51], v[56:57], v[90:91] op_sel:[1,0,0] op_sel_hi:[1,1,1]
	v_cndmask_b32_e64 v31, v31, v24, s[8:9]
	v_pk_fma_f32 v[2:3], v[44:45], v[22:23], v[84:85] op_sel:[0,0,0] op_sel_hi:[0,1,1] neg_lo:[1,0,0] neg_hi:[1,0,0]
	v_pk_fma_f32 v[4:5], v[44:45], v[22:23], v[86:87] op_sel:[1,0,0] op_sel_hi:[1,1,1] neg_lo:[1,0,0] neg_hi:[1,0,0]
	v_pk_fma_f32 v[6:7], v[46:47], v[22:23], v[88:89] op_sel:[0,0,0] op_sel_hi:[0,1,1] neg_lo:[1,0,0] neg_hi:[1,0,0]
	v_pk_fma_f32 v[8:9], v[46:47], v[22:23], v[90:91] op_sel:[1,0,0] op_sel_hi:[1,1,1] neg_lo:[1,0,0] neg_hi:[1,0,0]
	s_waitcnt lgkmcnt(0)
	ds_read_b128 v[36:39], v20 offset:4608
	ds_read_b128 v[40:43], v20 offset:12800
	ds_read_b64 v[56:57], v21 offset:45568
	ds_read_b128 v[48:51], v20 offset:29184
	ds_read_b128 v[44:47], v20 offset:20992
	v_pk_mul_f32 v[22:23], v[2:3], v[60:61] op_sel:[0,0] op_sel_hi:[1,0]
	v_pk_mul_f32 v[24:25], v[2:3], v[52:53] op_sel:[0,0] op_sel_hi:[1,0]
	v_pk_fma_f32 v[22:23], v[4:5], v[60:61], v[22:23] op_sel:[0,1,0] op_sel_hi:[1,1,1]
	v_pk_fma_f32 v[24:25], v[4:5], v[52:53], v[24:25] op_sel:[0,1,0] op_sel_hi:[1,1,1]
	v_pk_fma_f32 v[22:23], v[6:7], v[62:63], v[22:23] op_sel:[0,0,0] op_sel_hi:[1,0,1]
	v_pk_fma_f32 v[24:25], v[6:7], v[54:55], v[24:25] op_sel:[0,0,0] op_sel_hi:[1,0,1]
	v_pk_fma_f32 v[22:23], v[8:9], v[62:63], v[22:23] op_sel:[0,1,0] op_sel_hi:[1,1,1]
	v_pk_fma_f32 v[24:25], v[8:9], v[54:55], v[24:25] op_sel:[0,1,0] op_sel_hi:[1,1,1]
	ds_read_b128 v[52:55], v20 offset:37376
	v_add_f32_dpp v28, v28, v28 row_ror:12 row_mask:0xf bank_mask:0x5
	v_add_f32_dpp v29, v29, v29 row_ror:4 row_mask:0xf bank_mask:0xa
	v_add_f32_dpp v22, v22, v22 quad_perm:[1,0,3,2] row_mask:0xf bank_mask:0xf
	v_add_f32_dpp v23, v23, v23 quad_perm:[1,0,3,2] row_mask:0xf bank_mask:0xf
	v_pk_mul_f32 v[84:85], v[2:3], v[64:65] op_sel:[0,0] op_sel_hi:[1,0]
	v_pk_mul_f32 v[86:87], v[4:5], v[64:65] op_sel:[0,1] op_sel_hi:[1,1]
	v_add_f32_dpp v58, v58, v58 row_ror:12 row_mask:0xf bank_mask:0x5
	v_add_f32_dpp v22, v22, v22 quad_perm:[2,3,0,1] row_mask:0xf bank_mask:0xf
	v_add_f32_dpp v23, v23, v23 quad_perm:[2,3,0,1] row_mask:0xf bank_mask:0xf
	v_pk_mul_f32 v[88:89], v[6:7], v[66:67] op_sel:[0,0] op_sel_hi:[1,0]
	v_pk_mul_f32 v[90:91], v[8:9], v[66:67] op_sel:[0,1] op_sel_hi:[1,1]
	v_add_f32_dpp v59, v59, v59 row_ror:4 row_mask:0xf bank_mask:0xa
	v_add_f32_dpp v22, v22, v22 row_half_mirror row_mask:0xf bank_mask:0xf
	v_add_f32_dpp v23, v23, v23 row_half_mirror row_mask:0xf bank_mask:0xf
	v_pk_fma_f32 v[84:85], v[72:73], v[80:81], v[84:85] op_sel:[0,0,0] op_sel_hi:[0,1,1]
	v_pk_fma_f32 v[86:87], v[72:73], v[80:81], v[86:87] op_sel:[1,0,0] op_sel_hi:[1,1,1]
	v_mov_b32_dpp v28, v29 quad_perm:[0,1,2,3] row_mask:0xf bank_mask:0xa
	v_add_f32_dpp v22, v22, v22 row_mirror row_mask:0xf bank_mask:0xf
	v_add_f32_dpp v23, v23, v23 row_mirror row_mask:0xf bank_mask:0xf
	v_pk_fma_f32 v[88:89], v[74:75], v[80:81], v[88:89] op_sel:[0,0,0] op_sel_hi:[0,1,1]
	v_pk_fma_f32 v[90:91], v[74:75], v[80:81], v[90:91] op_sel:[1,0,0] op_sel_hi:[1,1,1]
	v_mov_b32_dpp v58, v59 quad_perm:[0,1,2,3] row_mask:0xf bank_mask:0xa
	v_pk_fma_f32 v[2:3], v[68:69], v[22:23], v[84:85] op_sel:[0,0,0] op_sel_hi:[0,1,1] neg_lo:[1,0,0] neg_hi:[1,0,0]
	v_pk_fma_f32 v[4:5], v[68:69], v[22:23], v[86:87] op_sel:[1,0,0] op_sel_hi:[1,1,1] neg_lo:[1,0,0] neg_hi:[1,0,0]
	v_pk_fma_f32 v[6:7], v[70:71], v[22:23], v[88:89] op_sel:[0,0,0] op_sel_hi:[0,1,1] neg_lo:[1,0,0] neg_hi:[1,0,0]
	v_pk_fma_f32 v[8:9], v[70:71], v[22:23], v[90:91] op_sel:[1,0,0] op_sel_hi:[1,1,1] neg_lo:[1,0,0] neg_hi:[1,0,0]
	s_waitcnt lgkmcnt(0)
	ds_read_b128 v[60:63], v20 offset:4864
	ds_read_b128 v[64:67], v20 offset:13056
	ds_read_b64 v[80:81], v21 offset:45824
	ds_read_b128 v[72:75], v20 offset:29440
	ds_read_b128 v[68:71], v20 offset:21248
	v_pk_mul_f32 v[22:23], v[2:3], v[36:37] op_sel:[0,0] op_sel_hi:[1,0]
	v_pk_mul_f32 v[26:27], v[2:3], v[76:77] op_sel:[0,0] op_sel_hi:[1,0]
	v_pk_fma_f32 v[22:23], v[4:5], v[36:37], v[22:23] op_sel:[0,1,0] op_sel_hi:[1,1,1]
	v_pk_fma_f32 v[26:27], v[4:5], v[76:77], v[26:27] op_sel:[0,1,0] op_sel_hi:[1,1,1]
	v_pk_fma_f32 v[22:23], v[6:7], v[38:39], v[22:23] op_sel:[0,0,0] op_sel_hi:[1,0,1]
	v_pk_fma_f32 v[26:27], v[6:7], v[78:79], v[26:27] op_sel:[0,0,0] op_sel_hi:[1,0,1]
	v_pk_fma_f32 v[22:23], v[8:9], v[38:39], v[22:23] op_sel:[0,1,0] op_sel_hi:[1,1,1]
	v_pk_fma_f32 v[26:27], v[8:9], v[78:79], v[26:27] op_sel:[0,1,0] op_sel_hi:[1,1,1]
	ds_read_b128 v[76:79], v20 offset:37632
	v_add_f32_dpp v28, v28, v28 row_ror:8 row_mask:0xf bank_mask:0x3
	v_add_f32_dpp v58, v58, v58 row_ror:8 row_mask:0xf bank_mask:0xc
	v_add_f32_dpp v22, v22, v22 quad_perm:[1,0,3,2] row_mask:0xf bank_mask:0xf
	v_add_f32_dpp v23, v23, v23 quad_perm:[1,0,3,2] row_mask:0xf bank_mask:0xf
	v_pk_mul_f32 v[84:85], v[2:3], v[40:41] op_sel:[0,0] op_sel_hi:[1,0]
	v_pk_mul_f32 v[86:87], v[4:5], v[40:41] op_sel:[0,1] op_sel_hi:[1,1]
	v_mov_b32_dpp v28, v58 quad_perm:[0,1,2,3] row_mask:0xf bank_mask:0xc
	v_add_f32_dpp v22, v22, v22 quad_perm:[2,3,0,1] row_mask:0xf bank_mask:0xf
	v_add_f32_dpp v23, v23, v23 quad_perm:[2,3,0,1] row_mask:0xf bank_mask:0xf
	v_pk_mul_f32 v[88:89], v[6:7], v[42:43] op_sel:[0,0] op_sel_hi:[1,0]
	v_pk_mul_f32 v[90:91], v[8:9], v[42:43] op_sel:[0,1] op_sel_hi:[1,1]
	v_add_f32_dpp v28, v28, v28 quad_perm:[1,0,3,2] row_mask:0xf bank_mask:0xf
	v_add_f32_dpp v22, v22, v22 row_half_mirror row_mask:0xf bank_mask:0xf
	v_add_f32_dpp v23, v23, v23 row_half_mirror row_mask:0xf bank_mask:0xf
	v_pk_fma_f32 v[84:85], v[48:49], v[56:57], v[84:85] op_sel:[0,0,0] op_sel_hi:[0,1,1]
	v_pk_fma_f32 v[86:87], v[48:49], v[56:57], v[86:87] op_sel:[1,0,0] op_sel_hi:[1,1,1]
	v_add_f32_dpp v28, v28, v28 quad_perm:[2,3,0,1] row_mask:0xf bank_mask:0xf
	v_add_f32_dpp v22, v22, v22 row_mirror row_mask:0xf bank_mask:0xf
	v_add_f32_dpp v23, v23, v23 row_mirror row_mask:0xf bank_mask:0xf
	v_pk_fma_f32 v[88:89], v[50:51], v[56:57], v[88:89] op_sel:[0,0,0] op_sel_hi:[0,1,1]
	v_pk_fma_f32 v[90:91], v[50:51], v[56:57], v[90:91] op_sel:[1,0,0] op_sel_hi:[1,1,1]
	v_cndmask_b32_e64 v31, v31, v28, s[10:11]
	v_pk_fma_f32 v[2:3], v[44:45], v[22:23], v[84:85] op_sel:[0,0,0] op_sel_hi:[0,1,1] neg_lo:[1,0,0] neg_hi:[1,0,0]
	v_pk_fma_f32 v[4:5], v[44:45], v[22:23], v[86:87] op_sel:[1,0,0] op_sel_hi:[1,1,1] neg_lo:[1,0,0] neg_hi:[1,0,0]
	v_pk_fma_f32 v[6:7], v[46:47], v[22:23], v[88:89] op_sel:[0,0,0] op_sel_hi:[0,1,1] neg_lo:[1,0,0] neg_hi:[1,0,0]
	v_pk_fma_f32 v[8:9], v[46:47], v[22:23], v[90:91] op_sel:[1,0,0] op_sel_hi:[1,1,1] neg_lo:[1,0,0] neg_hi:[1,0,0]
	s_waitcnt lgkmcnt(0)
	ds_read_b128 v[36:39], v20 offset:5120
	ds_read_b128 v[40:43], v20 offset:13312
	ds_read_b64 v[56:57], v21 offset:46080
	ds_read_b128 v[48:51], v20 offset:29696
	ds_read_b128 v[44:47], v20 offset:21504
	v_pk_mul_f32 v[22:23], v[2:3], v[60:61] op_sel:[0,0] op_sel_hi:[1,0]
	v_pk_mul_f32 v[28:29], v[2:3], v[52:53] op_sel:[0,0] op_sel_hi:[1,0]
	v_pk_fma_f32 v[22:23], v[4:5], v[60:61], v[22:23] op_sel:[0,1,0] op_sel_hi:[1,1,1]
	v_pk_fma_f32 v[28:29], v[4:5], v[52:53], v[28:29] op_sel:[0,1,0] op_sel_hi:[1,1,1]
	v_pk_fma_f32 v[22:23], v[6:7], v[62:63], v[22:23] op_sel:[0,0,0] op_sel_hi:[1,0,1]
	v_pk_fma_f32 v[28:29], v[6:7], v[54:55], v[28:29] op_sel:[0,0,0] op_sel_hi:[1,0,1]
	v_pk_fma_f32 v[22:23], v[8:9], v[62:63], v[22:23] op_sel:[0,1,0] op_sel_hi:[1,1,1]
	v_pk_fma_f32 v[28:29], v[8:9], v[54:55], v[28:29] op_sel:[0,1,0] op_sel_hi:[1,1,1]
	ds_read_b128 v[52:55], v20 offset:37888
	v_add_f32_dpp v24, v24, v24 row_ror:12 row_mask:0xf bank_mask:0x5
	v_add_f32_dpp v25, v25, v25 row_ror:4 row_mask:0xf bank_mask:0xa
	v_add_f32_dpp v22, v22, v22 quad_perm:[1,0,3,2] row_mask:0xf bank_mask:0xf
	v_add_f32_dpp v23, v23, v23 quad_perm:[1,0,3,2] row_mask:0xf bank_mask:0xf
	v_pk_mul_f32 v[84:85], v[2:3], v[64:65] op_sel:[0,0] op_sel_hi:[1,0]
	v_pk_mul_f32 v[86:87], v[4:5], v[64:65] op_sel:[0,1] op_sel_hi:[1,1]
	v_add_f32_dpp v26, v26, v26 row_ror:12 row_mask:0xf bank_mask:0x5
	v_add_f32_dpp v22, v22, v22 quad_perm:[2,3,0,1] row_mask:0xf bank_mask:0xf
	v_add_f32_dpp v23, v23, v23 quad_perm:[2,3,0,1] row_mask:0xf bank_mask:0xf
	v_pk_mul_f32 v[88:89], v[6:7], v[66:67] op_sel:[0,0] op_sel_hi:[1,0]
	v_pk_mul_f32 v[90:91], v[8:9], v[66:67] op_sel:[0,1] op_sel_hi:[1,1]
	v_add_f32_dpp v27, v27, v27 row_ror:4 row_mask:0xf bank_mask:0xa
	v_add_f32_dpp v22, v22, v22 row_half_mirror row_mask:0xf bank_mask:0xf
	v_add_f32_dpp v23, v23, v23 row_half_mirror row_mask:0xf bank_mask:0xf
	v_pk_fma_f32 v[84:85], v[72:73], v[80:81], v[84:85] op_sel:[0,0,0] op_sel_hi:[0,1,1]
	v_pk_fma_f32 v[86:87], v[72:73], v[80:81], v[86:87] op_sel:[1,0,0] op_sel_hi:[1,1,1]
	v_mov_b32_dpp v24, v25 quad_perm:[0,1,2,3] row_mask:0xf bank_mask:0xa
	v_add_f32_dpp v22, v22, v22 row_mirror row_mask:0xf bank_mask:0xf
	v_add_f32_dpp v23, v23, v23 row_mirror row_mask:0xf bank_mask:0xf
	v_pk_fma_f32 v[88:89], v[74:75], v[80:81], v[88:89] op_sel:[0,0,0] op_sel_hi:[0,1,1]
	v_pk_fma_f32 v[90:91], v[74:75], v[80:81], v[90:91] op_sel:[1,0,0] op_sel_hi:[1,1,1]
	v_mov_b32_dpp v26, v27 quad_perm:[0,1,2,3] row_mask:0xf bank_mask:0xa
	v_pk_fma_f32 v[2:3], v[68:69], v[22:23], v[84:85] op_sel:[0,0,0] op_sel_hi:[0,1,1] neg_lo:[1,0,0] neg_hi:[1,0,0]
	v_pk_fma_f32 v[4:5], v[68:69], v[22:23], v[86:87] op_sel:[1,0,0] op_sel_hi:[1,1,1] neg_lo:[1,0,0] neg_hi:[1,0,0]
	v_pk_fma_f32 v[6:7], v[70:71], v[22:23], v[88:89] op_sel:[0,0,0] op_sel_hi:[0,1,1] neg_lo:[1,0,0] neg_hi:[1,0,0]
	v_pk_fma_f32 v[8:9], v[70:71], v[22:23], v[90:91] op_sel:[1,0,0] op_sel_hi:[1,1,1] neg_lo:[1,0,0] neg_hi:[1,0,0]
	s_waitcnt lgkmcnt(0)
	ds_read_b128 v[60:63], v20 offset:5376
	ds_read_b128 v[64:67], v20 offset:13568
	ds_read_b64 v[80:81], v21 offset:46336
	ds_read_b128 v[72:75], v20 offset:29952
	ds_read_b128 v[68:71], v20 offset:21760
	v_pk_mul_f32 v[22:23], v[2:3], v[36:37] op_sel:[0,0] op_sel_hi:[1,0]
	v_pk_mul_f32 v[58:59], v[2:3], v[76:77] op_sel:[0,0] op_sel_hi:[1,0]
	v_pk_fma_f32 v[22:23], v[4:5], v[36:37], v[22:23] op_sel:[0,1,0] op_sel_hi:[1,1,1]
	v_pk_fma_f32 v[58:59], v[4:5], v[76:77], v[58:59] op_sel:[0,1,0] op_sel_hi:[1,1,1]
	v_pk_fma_f32 v[22:23], v[6:7], v[38:39], v[22:23] op_sel:[0,0,0] op_sel_hi:[1,0,1]
	v_pk_fma_f32 v[58:59], v[6:7], v[78:79], v[58:59] op_sel:[0,0,0] op_sel_hi:[1,0,1]
	v_pk_fma_f32 v[22:23], v[8:9], v[38:39], v[22:23] op_sel:[0,1,0] op_sel_hi:[1,1,1]
	v_pk_fma_f32 v[58:59], v[8:9], v[78:79], v[58:59] op_sel:[0,1,0] op_sel_hi:[1,1,1]
	ds_read_b128 v[76:79], v20 offset:38144
	v_add_f32_dpp v24, v24, v24 row_ror:8 row_mask:0xf bank_mask:0x3
	v_add_f32_dpp v26, v26, v26 row_ror:8 row_mask:0xf bank_mask:0xc
	v_add_f32_dpp v22, v22, v22 quad_perm:[1,0,3,2] row_mask:0xf bank_mask:0xf
	v_add_f32_dpp v23, v23, v23 quad_perm:[1,0,3,2] row_mask:0xf bank_mask:0xf
	v_pk_mul_f32 v[84:85], v[2:3], v[40:41] op_sel:[0,0] op_sel_hi:[1,0]
	v_pk_mul_f32 v[86:87], v[4:5], v[40:41] op_sel:[0,1] op_sel_hi:[1,1]
	v_mov_b32_dpp v24, v26 quad_perm:[0,1,2,3] row_mask:0xf bank_mask:0xc
	v_add_f32_dpp v22, v22, v22 quad_perm:[2,3,0,1] row_mask:0xf bank_mask:0xf
	v_add_f32_dpp v23, v23, v23 quad_perm:[2,3,0,1] row_mask:0xf bank_mask:0xf
	v_pk_mul_f32 v[88:89], v[6:7], v[42:43] op_sel:[0,0] op_sel_hi:[1,0]
	v_pk_mul_f32 v[90:91], v[8:9], v[42:43] op_sel:[0,1] op_sel_hi:[1,1]
	v_add_f32_dpp v24, v24, v24 quad_perm:[1,0,3,2] row_mask:0xf bank_mask:0xf
	v_add_f32_dpp v22, v22, v22 row_half_mirror row_mask:0xf bank_mask:0xf
	v_add_f32_dpp v23, v23, v23 row_half_mirror row_mask:0xf bank_mask:0xf
	v_pk_fma_f32 v[84:85], v[48:49], v[56:57], v[84:85] op_sel:[0,0,0] op_sel_hi:[0,1,1]
	v_pk_fma_f32 v[86:87], v[48:49], v[56:57], v[86:87] op_sel:[1,0,0] op_sel_hi:[1,1,1]
	v_add_f32_dpp v24, v24, v24 quad_perm:[2,3,0,1] row_mask:0xf bank_mask:0xf
	v_add_f32_dpp v22, v22, v22 row_mirror row_mask:0xf bank_mask:0xf
	v_add_f32_dpp v23, v23, v23 row_mirror row_mask:0xf bank_mask:0xf
	v_pk_fma_f32 v[88:89], v[50:51], v[56:57], v[88:89] op_sel:[0,0,0] op_sel_hi:[0,1,1]
	v_pk_fma_f32 v[90:91], v[50:51], v[56:57], v[90:91] op_sel:[1,0,0] op_sel_hi:[1,1,1]
	v_cndmask_b32_e64 v32, 0, v24, s[0:1]
	v_pk_fma_f32 v[2:3], v[44:45], v[22:23], v[84:85] op_sel:[0,0,0] op_sel_hi:[0,1,1] neg_lo:[1,0,0] neg_hi:[1,0,0]
	v_pk_fma_f32 v[4:5], v[44:45], v[22:23], v[86:87] op_sel:[1,0,0] op_sel_hi:[1,1,1] neg_lo:[1,0,0] neg_hi:[1,0,0]
	v_pk_fma_f32 v[6:7], v[46:47], v[22:23], v[88:89] op_sel:[0,0,0] op_sel_hi:[0,1,1] neg_lo:[1,0,0] neg_hi:[1,0,0]
	v_pk_fma_f32 v[8:9], v[46:47], v[22:23], v[90:91] op_sel:[1,0,0] op_sel_hi:[1,1,1] neg_lo:[1,0,0] neg_hi:[1,0,0]
	s_waitcnt lgkmcnt(0)
	ds_read_b128 v[36:39], v20 offset:5632
	ds_read_b128 v[40:43], v20 offset:13824
	ds_read_b64 v[56:57], v21 offset:46592
	ds_read_b128 v[48:51], v20 offset:30208
	ds_read_b128 v[44:47], v20 offset:22016
	v_pk_mul_f32 v[22:23], v[2:3], v[60:61] op_sel:[0,0] op_sel_hi:[1,0]
	v_pk_mul_f32 v[24:25], v[2:3], v[52:53] op_sel:[0,0] op_sel_hi:[1,0]
	v_pk_fma_f32 v[22:23], v[4:5], v[60:61], v[22:23] op_sel:[0,1,0] op_sel_hi:[1,1,1]
	v_pk_fma_f32 v[24:25], v[4:5], v[52:53], v[24:25] op_sel:[0,1,0] op_sel_hi:[1,1,1]
	v_pk_fma_f32 v[22:23], v[6:7], v[62:63], v[22:23] op_sel:[0,0,0] op_sel_hi:[1,0,1]
	v_pk_fma_f32 v[24:25], v[6:7], v[54:55], v[24:25] op_sel:[0,0,0] op_sel_hi:[1,0,1]
	v_pk_fma_f32 v[22:23], v[8:9], v[62:63], v[22:23] op_sel:[0,1,0] op_sel_hi:[1,1,1]
	v_pk_fma_f32 v[24:25], v[8:9], v[54:55], v[24:25] op_sel:[0,1,0] op_sel_hi:[1,1,1]
	ds_read_b128 v[52:55], v20 offset:38400
	v_add_f32_dpp v28, v28, v28 row_ror:12 row_mask:0xf bank_mask:0x5
	v_add_f32_dpp v29, v29, v29 row_ror:4 row_mask:0xf bank_mask:0xa
	v_add_f32_dpp v22, v22, v22 quad_perm:[1,0,3,2] row_mask:0xf bank_mask:0xf
	v_add_f32_dpp v23, v23, v23 quad_perm:[1,0,3,2] row_mask:0xf bank_mask:0xf
	v_pk_mul_f32 v[84:85], v[2:3], v[64:65] op_sel:[0,0] op_sel_hi:[1,0]
	v_pk_mul_f32 v[86:87], v[4:5], v[64:65] op_sel:[0,1] op_sel_hi:[1,1]
	v_add_f32_dpp v58, v58, v58 row_ror:12 row_mask:0xf bank_mask:0x5
	v_add_f32_dpp v22, v22, v22 quad_perm:[2,3,0,1] row_mask:0xf bank_mask:0xf
	v_add_f32_dpp v23, v23, v23 quad_perm:[2,3,0,1] row_mask:0xf bank_mask:0xf
	v_pk_mul_f32 v[88:89], v[6:7], v[66:67] op_sel:[0,0] op_sel_hi:[1,0]
	v_pk_mul_f32 v[90:91], v[8:9], v[66:67] op_sel:[0,1] op_sel_hi:[1,1]
	v_add_f32_dpp v59, v59, v59 row_ror:4 row_mask:0xf bank_mask:0xa
	v_add_f32_dpp v22, v22, v22 row_half_mirror row_mask:0xf bank_mask:0xf
	v_add_f32_dpp v23, v23, v23 row_half_mirror row_mask:0xf bank_mask:0xf
	v_pk_fma_f32 v[84:85], v[72:73], v[80:81], v[84:85] op_sel:[0,0,0] op_sel_hi:[0,1,1]
	v_pk_fma_f32 v[86:87], v[72:73], v[80:81], v[86:87] op_sel:[1,0,0] op_sel_hi:[1,1,1]
	v_mov_b32_dpp v28, v29 quad_perm:[0,1,2,3] row_mask:0xf bank_mask:0xa
	v_add_f32_dpp v22, v22, v22 row_mirror row_mask:0xf bank_mask:0xf
	v_add_f32_dpp v23, v23, v23 row_mirror row_mask:0xf bank_mask:0xf
	v_pk_fma_f32 v[88:89], v[74:75], v[80:81], v[88:89] op_sel:[0,0,0] op_sel_hi:[0,1,1]
	v_pk_fma_f32 v[90:91], v[74:75], v[80:81], v[90:91] op_sel:[1,0,0] op_sel_hi:[1,1,1]
	v_mov_b32_dpp v58, v59 quad_perm:[0,1,2,3] row_mask:0xf bank_mask:0xa
	v_pk_fma_f32 v[2:3], v[68:69], v[22:23], v[84:85] op_sel:[0,0,0] op_sel_hi:[0,1,1] neg_lo:[1,0,0] neg_hi:[1,0,0]
	v_pk_fma_f32 v[4:5], v[68:69], v[22:23], v[86:87] op_sel:[1,0,0] op_sel_hi:[1,1,1] neg_lo:[1,0,0] neg_hi:[1,0,0]
	v_pk_fma_f32 v[6:7], v[70:71], v[22:23], v[88:89] op_sel:[0,0,0] op_sel_hi:[0,1,1] neg_lo:[1,0,0] neg_hi:[1,0,0]
	v_pk_fma_f32 v[8:9], v[70:71], v[22:23], v[90:91] op_sel:[1,0,0] op_sel_hi:[1,1,1] neg_lo:[1,0,0] neg_hi:[1,0,0]
	s_waitcnt lgkmcnt(0)
	ds_read_b128 v[60:63], v20 offset:5888
	ds_read_b128 v[64:67], v20 offset:14080
	ds_read_b64 v[80:81], v21 offset:46848
	ds_read_b128 v[72:75], v20 offset:30464
	ds_read_b128 v[68:71], v20 offset:22272
	v_pk_mul_f32 v[22:23], v[2:3], v[36:37] op_sel:[0,0] op_sel_hi:[1,0]
	v_pk_mul_f32 v[26:27], v[2:3], v[76:77] op_sel:[0,0] op_sel_hi:[1,0]
	v_pk_fma_f32 v[22:23], v[4:5], v[36:37], v[22:23] op_sel:[0,1,0] op_sel_hi:[1,1,1]
	v_pk_fma_f32 v[26:27], v[4:5], v[76:77], v[26:27] op_sel:[0,1,0] op_sel_hi:[1,1,1]
	v_pk_fma_f32 v[22:23], v[6:7], v[38:39], v[22:23] op_sel:[0,0,0] op_sel_hi:[1,0,1]
	v_pk_fma_f32 v[26:27], v[6:7], v[78:79], v[26:27] op_sel:[0,0,0] op_sel_hi:[1,0,1]
	v_pk_fma_f32 v[22:23], v[8:9], v[38:39], v[22:23] op_sel:[0,1,0] op_sel_hi:[1,1,1]
	v_pk_fma_f32 v[26:27], v[8:9], v[78:79], v[26:27] op_sel:[0,1,0] op_sel_hi:[1,1,1]
	ds_read_b128 v[76:79], v20 offset:38656
	v_add_f32_dpp v28, v28, v28 row_ror:8 row_mask:0xf bank_mask:0x3
	v_add_f32_dpp v58, v58, v58 row_ror:8 row_mask:0xf bank_mask:0xc
	v_add_f32_dpp v22, v22, v22 quad_perm:[1,0,3,2] row_mask:0xf bank_mask:0xf
	v_add_f32_dpp v23, v23, v23 quad_perm:[1,0,3,2] row_mask:0xf bank_mask:0xf
	v_pk_mul_f32 v[84:85], v[2:3], v[40:41] op_sel:[0,0] op_sel_hi:[1,0]
	v_pk_mul_f32 v[86:87], v[4:5], v[40:41] op_sel:[0,1] op_sel_hi:[1,1]
	v_mov_b32_dpp v28, v58 quad_perm:[0,1,2,3] row_mask:0xf bank_mask:0xc
	v_add_f32_dpp v22, v22, v22 quad_perm:[2,3,0,1] row_mask:0xf bank_mask:0xf
	v_add_f32_dpp v23, v23, v23 quad_perm:[2,3,0,1] row_mask:0xf bank_mask:0xf
	v_pk_mul_f32 v[88:89], v[6:7], v[42:43] op_sel:[0,0] op_sel_hi:[1,0]
	v_pk_mul_f32 v[90:91], v[8:9], v[42:43] op_sel:[0,1] op_sel_hi:[1,1]
	v_add_f32_dpp v28, v28, v28 quad_perm:[1,0,3,2] row_mask:0xf bank_mask:0xf
	v_add_f32_dpp v22, v22, v22 row_half_mirror row_mask:0xf bank_mask:0xf
	v_add_f32_dpp v23, v23, v23 row_half_mirror row_mask:0xf bank_mask:0xf
	v_pk_fma_f32 v[84:85], v[48:49], v[56:57], v[84:85] op_sel:[0,0,0] op_sel_hi:[0,1,1]
	v_pk_fma_f32 v[86:87], v[48:49], v[56:57], v[86:87] op_sel:[1,0,0] op_sel_hi:[1,1,1]
	v_add_f32_dpp v28, v28, v28 quad_perm:[2,3,0,1] row_mask:0xf bank_mask:0xf
	v_add_f32_dpp v22, v22, v22 row_mirror row_mask:0xf bank_mask:0xf
	v_add_f32_dpp v23, v23, v23 row_mirror row_mask:0xf bank_mask:0xf
	v_pk_fma_f32 v[88:89], v[50:51], v[56:57], v[88:89] op_sel:[0,0,0] op_sel_hi:[0,1,1]
	v_pk_fma_f32 v[90:91], v[50:51], v[56:57], v[90:91] op_sel:[1,0,0] op_sel_hi:[1,1,1]
	v_cndmask_b32_e64 v32, v32, v28, s[6:7]
	v_pk_fma_f32 v[2:3], v[44:45], v[22:23], v[84:85] op_sel:[0,0,0] op_sel_hi:[0,1,1] neg_lo:[1,0,0] neg_hi:[1,0,0]
	v_pk_fma_f32 v[4:5], v[44:45], v[22:23], v[86:87] op_sel:[1,0,0] op_sel_hi:[1,1,1] neg_lo:[1,0,0] neg_hi:[1,0,0]
	v_pk_fma_f32 v[6:7], v[46:47], v[22:23], v[88:89] op_sel:[0,0,0] op_sel_hi:[0,1,1] neg_lo:[1,0,0] neg_hi:[1,0,0]
	v_pk_fma_f32 v[8:9], v[46:47], v[22:23], v[90:91] op_sel:[1,0,0] op_sel_hi:[1,1,1] neg_lo:[1,0,0] neg_hi:[1,0,0]
	s_waitcnt lgkmcnt(0)
	ds_read_b128 v[36:39], v20 offset:6144
	ds_read_b128 v[40:43], v20 offset:14336
	ds_read_b64 v[56:57], v21 offset:47104
	ds_read_b128 v[48:51], v20 offset:30720
	ds_read_b128 v[44:47], v20 offset:22528
	v_pk_mul_f32 v[22:23], v[2:3], v[60:61] op_sel:[0,0] op_sel_hi:[1,0]
	v_pk_mul_f32 v[28:29], v[2:3], v[52:53] op_sel:[0,0] op_sel_hi:[1,0]
	v_pk_fma_f32 v[22:23], v[4:5], v[60:61], v[22:23] op_sel:[0,1,0] op_sel_hi:[1,1,1]
	v_pk_fma_f32 v[28:29], v[4:5], v[52:53], v[28:29] op_sel:[0,1,0] op_sel_hi:[1,1,1]
	v_pk_fma_f32 v[22:23], v[6:7], v[62:63], v[22:23] op_sel:[0,0,0] op_sel_hi:[1,0,1]
	v_pk_fma_f32 v[28:29], v[6:7], v[54:55], v[28:29] op_sel:[0,0,0] op_sel_hi:[1,0,1]
	v_pk_fma_f32 v[22:23], v[8:9], v[62:63], v[22:23] op_sel:[0,1,0] op_sel_hi:[1,1,1]
	v_pk_fma_f32 v[28:29], v[8:9], v[54:55], v[28:29] op_sel:[0,1,0] op_sel_hi:[1,1,1]
	ds_read_b128 v[52:55], v20 offset:38912
	v_add_f32_dpp v24, v24, v24 row_ror:12 row_mask:0xf bank_mask:0x5
	v_add_f32_dpp v25, v25, v25 row_ror:4 row_mask:0xf bank_mask:0xa
	v_add_f32_dpp v22, v22, v22 quad_perm:[1,0,3,2] row_mask:0xf bank_mask:0xf
	v_add_f32_dpp v23, v23, v23 quad_perm:[1,0,3,2] row_mask:0xf bank_mask:0xf
	v_pk_mul_f32 v[84:85], v[2:3], v[64:65] op_sel:[0,0] op_sel_hi:[1,0]
	v_pk_mul_f32 v[86:87], v[4:5], v[64:65] op_sel:[0,1] op_sel_hi:[1,1]
	v_add_f32_dpp v26, v26, v26 row_ror:12 row_mask:0xf bank_mask:0x5
	v_add_f32_dpp v22, v22, v22 quad_perm:[2,3,0,1] row_mask:0xf bank_mask:0xf
	v_add_f32_dpp v23, v23, v23 quad_perm:[2,3,0,1] row_mask:0xf bank_mask:0xf
	v_pk_mul_f32 v[88:89], v[6:7], v[66:67] op_sel:[0,0] op_sel_hi:[1,0]
	v_pk_mul_f32 v[90:91], v[8:9], v[66:67] op_sel:[0,1] op_sel_hi:[1,1]
	v_add_f32_dpp v27, v27, v27 row_ror:4 row_mask:0xf bank_mask:0xa
	v_add_f32_dpp v22, v22, v22 row_half_mirror row_mask:0xf bank_mask:0xf
	v_add_f32_dpp v23, v23, v23 row_half_mirror row_mask:0xf bank_mask:0xf
	v_pk_fma_f32 v[84:85], v[72:73], v[80:81], v[84:85] op_sel:[0,0,0] op_sel_hi:[0,1,1]
	v_pk_fma_f32 v[86:87], v[72:73], v[80:81], v[86:87] op_sel:[1,0,0] op_sel_hi:[1,1,1]
	v_mov_b32_dpp v24, v25 quad_perm:[0,1,2,3] row_mask:0xf bank_mask:0xa
	v_add_f32_dpp v22, v22, v22 row_mirror row_mask:0xf bank_mask:0xf
	v_add_f32_dpp v23, v23, v23 row_mirror row_mask:0xf bank_mask:0xf
	v_pk_fma_f32 v[88:89], v[74:75], v[80:81], v[88:89] op_sel:[0,0,0] op_sel_hi:[0,1,1]
	v_pk_fma_f32 v[90:91], v[74:75], v[80:81], v[90:91] op_sel:[1,0,0] op_sel_hi:[1,1,1]
	v_mov_b32_dpp v26, v27 quad_perm:[0,1,2,3] row_mask:0xf bank_mask:0xa
	v_pk_fma_f32 v[2:3], v[68:69], v[22:23], v[84:85] op_sel:[0,0,0] op_sel_hi:[0,1,1] neg_lo:[1,0,0] neg_hi:[1,0,0]
	v_pk_fma_f32 v[4:5], v[68:69], v[22:23], v[86:87] op_sel:[1,0,0] op_sel_hi:[1,1,1] neg_lo:[1,0,0] neg_hi:[1,0,0]
	v_pk_fma_f32 v[6:7], v[70:71], v[22:23], v[88:89] op_sel:[0,0,0] op_sel_hi:[0,1,1] neg_lo:[1,0,0] neg_hi:[1,0,0]
	v_pk_fma_f32 v[8:9], v[70:71], v[22:23], v[90:91] op_sel:[1,0,0] op_sel_hi:[1,1,1] neg_lo:[1,0,0] neg_hi:[1,0,0]
	s_waitcnt lgkmcnt(0)
	ds_read_b128 v[60:63], v20 offset:6400
	ds_read_b128 v[64:67], v20 offset:14592
	ds_read_b64 v[80:81], v21 offset:47360
	ds_read_b128 v[72:75], v20 offset:30976
	ds_read_b128 v[68:71], v20 offset:22784
	v_pk_mul_f32 v[22:23], v[2:3], v[36:37] op_sel:[0,0] op_sel_hi:[1,0]
	v_pk_mul_f32 v[58:59], v[2:3], v[76:77] op_sel:[0,0] op_sel_hi:[1,0]
	v_pk_fma_f32 v[22:23], v[4:5], v[36:37], v[22:23] op_sel:[0,1,0] op_sel_hi:[1,1,1]
	v_pk_fma_f32 v[58:59], v[4:5], v[76:77], v[58:59] op_sel:[0,1,0] op_sel_hi:[1,1,1]
	v_pk_fma_f32 v[22:23], v[6:7], v[38:39], v[22:23] op_sel:[0,0,0] op_sel_hi:[1,0,1]
	v_pk_fma_f32 v[58:59], v[6:7], v[78:79], v[58:59] op_sel:[0,0,0] op_sel_hi:[1,0,1]
	v_pk_fma_f32 v[22:23], v[8:9], v[38:39], v[22:23] op_sel:[0,1,0] op_sel_hi:[1,1,1]
	v_pk_fma_f32 v[58:59], v[8:9], v[78:79], v[58:59] op_sel:[0,1,0] op_sel_hi:[1,1,1]
	ds_read_b128 v[76:79], v20 offset:39168
	v_add_f32_dpp v24, v24, v24 row_ror:8 row_mask:0xf bank_mask:0x3
	v_add_f32_dpp v26, v26, v26 row_ror:8 row_mask:0xf bank_mask:0xc
	v_add_f32_dpp v22, v22, v22 quad_perm:[1,0,3,2] row_mask:0xf bank_mask:0xf
	v_add_f32_dpp v23, v23, v23 quad_perm:[1,0,3,2] row_mask:0xf bank_mask:0xf
	v_pk_mul_f32 v[84:85], v[2:3], v[40:41] op_sel:[0,0] op_sel_hi:[1,0]
	v_pk_mul_f32 v[86:87], v[4:5], v[40:41] op_sel:[0,1] op_sel_hi:[1,1]
	v_mov_b32_dpp v24, v26 quad_perm:[0,1,2,3] row_mask:0xf bank_mask:0xc
	v_add_f32_dpp v22, v22, v22 quad_perm:[2,3,0,1] row_mask:0xf bank_mask:0xf
	v_add_f32_dpp v23, v23, v23 quad_perm:[2,3,0,1] row_mask:0xf bank_mask:0xf
	v_pk_mul_f32 v[88:89], v[6:7], v[42:43] op_sel:[0,0] op_sel_hi:[1,0]
	v_pk_mul_f32 v[90:91], v[8:9], v[42:43] op_sel:[0,1] op_sel_hi:[1,1]
	v_add_f32_dpp v24, v24, v24 quad_perm:[1,0,3,2] row_mask:0xf bank_mask:0xf
	v_add_f32_dpp v22, v22, v22 row_half_mirror row_mask:0xf bank_mask:0xf
	v_add_f32_dpp v23, v23, v23 row_half_mirror row_mask:0xf bank_mask:0xf
	v_pk_fma_f32 v[84:85], v[48:49], v[56:57], v[84:85] op_sel:[0,0,0] op_sel_hi:[0,1,1]
	v_pk_fma_f32 v[86:87], v[48:49], v[56:57], v[86:87] op_sel:[1,0,0] op_sel_hi:[1,1,1]
	v_add_f32_dpp v24, v24, v24 quad_perm:[2,3,0,1] row_mask:0xf bank_mask:0xf
	v_add_f32_dpp v22, v22, v22 row_mirror row_mask:0xf bank_mask:0xf
	v_add_f32_dpp v23, v23, v23 row_mirror row_mask:0xf bank_mask:0xf
	v_pk_fma_f32 v[88:89], v[50:51], v[56:57], v[88:89] op_sel:[0,0,0] op_sel_hi:[0,1,1]
	v_pk_fma_f32 v[90:91], v[50:51], v[56:57], v[90:91] op_sel:[1,0,0] op_sel_hi:[1,1,1]
	v_cndmask_b32_e64 v32, v32, v24, s[8:9]
	v_pk_fma_f32 v[2:3], v[44:45], v[22:23], v[84:85] op_sel:[0,0,0] op_sel_hi:[0,1,1] neg_lo:[1,0,0] neg_hi:[1,0,0]
	v_pk_fma_f32 v[4:5], v[44:45], v[22:23], v[86:87] op_sel:[1,0,0] op_sel_hi:[1,1,1] neg_lo:[1,0,0] neg_hi:[1,0,0]
	v_pk_fma_f32 v[6:7], v[46:47], v[22:23], v[88:89] op_sel:[0,0,0] op_sel_hi:[0,1,1] neg_lo:[1,0,0] neg_hi:[1,0,0]
	v_pk_fma_f32 v[8:9], v[46:47], v[22:23], v[90:91] op_sel:[1,0,0] op_sel_hi:[1,1,1] neg_lo:[1,0,0] neg_hi:[1,0,0]
	s_waitcnt lgkmcnt(0)
	ds_read_b128 v[36:39], v20 offset:6656
	ds_read_b128 v[40:43], v20 offset:14848
	ds_read_b64 v[56:57], v21 offset:47616
	ds_read_b128 v[48:51], v20 offset:31232
	ds_read_b128 v[44:47], v20 offset:23040
	v_pk_mul_f32 v[22:23], v[2:3], v[60:61] op_sel:[0,0] op_sel_hi:[1,0]
	v_pk_mul_f32 v[24:25], v[2:3], v[52:53] op_sel:[0,0] op_sel_hi:[1,0]
	v_pk_fma_f32 v[22:23], v[4:5], v[60:61], v[22:23] op_sel:[0,1,0] op_sel_hi:[1,1,1]
	v_pk_fma_f32 v[24:25], v[4:5], v[52:53], v[24:25] op_sel:[0,1,0] op_sel_hi:[1,1,1]
	v_pk_fma_f32 v[22:23], v[6:7], v[62:63], v[22:23] op_sel:[0,0,0] op_sel_hi:[1,0,1]
	v_pk_fma_f32 v[24:25], v[6:7], v[54:55], v[24:25] op_sel:[0,0,0] op_sel_hi:[1,0,1]
	v_pk_fma_f32 v[22:23], v[8:9], v[62:63], v[22:23] op_sel:[0,1,0] op_sel_hi:[1,1,1]
	v_pk_fma_f32 v[24:25], v[8:9], v[54:55], v[24:25] op_sel:[0,1,0] op_sel_hi:[1,1,1]
	ds_read_b128 v[52:55], v20 offset:39424
	v_add_f32_dpp v28, v28, v28 row_ror:12 row_mask:0xf bank_mask:0x5
	v_add_f32_dpp v29, v29, v29 row_ror:4 row_mask:0xf bank_mask:0xa
	v_add_f32_dpp v22, v22, v22 quad_perm:[1,0,3,2] row_mask:0xf bank_mask:0xf
	v_add_f32_dpp v23, v23, v23 quad_perm:[1,0,3,2] row_mask:0xf bank_mask:0xf
	v_pk_mul_f32 v[84:85], v[2:3], v[64:65] op_sel:[0,0] op_sel_hi:[1,0]
	v_pk_mul_f32 v[86:87], v[4:5], v[64:65] op_sel:[0,1] op_sel_hi:[1,1]
	v_add_f32_dpp v58, v58, v58 row_ror:12 row_mask:0xf bank_mask:0x5
	v_add_f32_dpp v22, v22, v22 quad_perm:[2,3,0,1] row_mask:0xf bank_mask:0xf
	v_add_f32_dpp v23, v23, v23 quad_perm:[2,3,0,1] row_mask:0xf bank_mask:0xf
	v_pk_mul_f32 v[88:89], v[6:7], v[66:67] op_sel:[0,0] op_sel_hi:[1,0]
	v_pk_mul_f32 v[90:91], v[8:9], v[66:67] op_sel:[0,1] op_sel_hi:[1,1]
	v_add_f32_dpp v59, v59, v59 row_ror:4 row_mask:0xf bank_mask:0xa
	v_add_f32_dpp v22, v22, v22 row_half_mirror row_mask:0xf bank_mask:0xf
	v_add_f32_dpp v23, v23, v23 row_half_mirror row_mask:0xf bank_mask:0xf
	v_pk_fma_f32 v[84:85], v[72:73], v[80:81], v[84:85] op_sel:[0,0,0] op_sel_hi:[0,1,1]
	v_pk_fma_f32 v[86:87], v[72:73], v[80:81], v[86:87] op_sel:[1,0,0] op_sel_hi:[1,1,1]
	v_mov_b32_dpp v28, v29 quad_perm:[0,1,2,3] row_mask:0xf bank_mask:0xa
	v_add_f32_dpp v22, v22, v22 row_mirror row_mask:0xf bank_mask:0xf
	v_add_f32_dpp v23, v23, v23 row_mirror row_mask:0xf bank_mask:0xf
	v_pk_fma_f32 v[88:89], v[74:75], v[80:81], v[88:89] op_sel:[0,0,0] op_sel_hi:[0,1,1]
	v_pk_fma_f32 v[90:91], v[74:75], v[80:81], v[90:91] op_sel:[1,0,0] op_sel_hi:[1,1,1]
	v_mov_b32_dpp v58, v59 quad_perm:[0,1,2,3] row_mask:0xf bank_mask:0xa
	v_pk_fma_f32 v[2:3], v[68:69], v[22:23], v[84:85] op_sel:[0,0,0] op_sel_hi:[0,1,1] neg_lo:[1,0,0] neg_hi:[1,0,0]
	v_pk_fma_f32 v[4:5], v[68:69], v[22:23], v[86:87] op_sel:[1,0,0] op_sel_hi:[1,1,1] neg_lo:[1,0,0] neg_hi:[1,0,0]
	v_pk_fma_f32 v[6:7], v[70:71], v[22:23], v[88:89] op_sel:[0,0,0] op_sel_hi:[0,1,1] neg_lo:[1,0,0] neg_hi:[1,0,0]
	v_pk_fma_f32 v[8:9], v[70:71], v[22:23], v[90:91] op_sel:[1,0,0] op_sel_hi:[1,1,1] neg_lo:[1,0,0] neg_hi:[1,0,0]
	s_waitcnt lgkmcnt(0)
	ds_read_b128 v[60:63], v20 offset:6912
	ds_read_b128 v[64:67], v20 offset:15104
	ds_read_b64 v[80:81], v21 offset:47872
	ds_read_b128 v[72:75], v20 offset:31488
	ds_read_b128 v[68:71], v20 offset:23296
	v_pk_mul_f32 v[22:23], v[2:3], v[36:37] op_sel:[0,0] op_sel_hi:[1,0]
	v_pk_mul_f32 v[26:27], v[2:3], v[76:77] op_sel:[0,0] op_sel_hi:[1,0]
	v_pk_fma_f32 v[22:23], v[4:5], v[36:37], v[22:23] op_sel:[0,1,0] op_sel_hi:[1,1,1]
	v_pk_fma_f32 v[26:27], v[4:5], v[76:77], v[26:27] op_sel:[0,1,0] op_sel_hi:[1,1,1]
	v_pk_fma_f32 v[22:23], v[6:7], v[38:39], v[22:23] op_sel:[0,0,0] op_sel_hi:[1,0,1]
	v_pk_fma_f32 v[26:27], v[6:7], v[78:79], v[26:27] op_sel:[0,0,0] op_sel_hi:[1,0,1]
	v_pk_fma_f32 v[22:23], v[8:9], v[38:39], v[22:23] op_sel:[0,1,0] op_sel_hi:[1,1,1]
	v_pk_fma_f32 v[26:27], v[8:9], v[78:79], v[26:27] op_sel:[0,1,0] op_sel_hi:[1,1,1]
	ds_read_b128 v[76:79], v20 offset:39680
	v_add_f32_dpp v28, v28, v28 row_ror:8 row_mask:0xf bank_mask:0x3
	v_add_f32_dpp v58, v58, v58 row_ror:8 row_mask:0xf bank_mask:0xc
	v_add_f32_dpp v22, v22, v22 quad_perm:[1,0,3,2] row_mask:0xf bank_mask:0xf
	v_add_f32_dpp v23, v23, v23 quad_perm:[1,0,3,2] row_mask:0xf bank_mask:0xf
	v_pk_mul_f32 v[84:85], v[2:3], v[40:41] op_sel:[0,0] op_sel_hi:[1,0]
	v_pk_mul_f32 v[86:87], v[4:5], v[40:41] op_sel:[0,1] op_sel_hi:[1,1]
	v_mov_b32_dpp v28, v58 quad_perm:[0,1,2,3] row_mask:0xf bank_mask:0xc
	v_add_f32_dpp v22, v22, v22 quad_perm:[2,3,0,1] row_mask:0xf bank_mask:0xf
	v_add_f32_dpp v23, v23, v23 quad_perm:[2,3,0,1] row_mask:0xf bank_mask:0xf
	v_pk_mul_f32 v[88:89], v[6:7], v[42:43] op_sel:[0,0] op_sel_hi:[1,0]
	v_pk_mul_f32 v[90:91], v[8:9], v[42:43] op_sel:[0,1] op_sel_hi:[1,1]
	v_add_f32_dpp v28, v28, v28 quad_perm:[1,0,3,2] row_mask:0xf bank_mask:0xf
	v_add_f32_dpp v22, v22, v22 row_half_mirror row_mask:0xf bank_mask:0xf
	v_add_f32_dpp v23, v23, v23 row_half_mirror row_mask:0xf bank_mask:0xf
	v_pk_fma_f32 v[84:85], v[48:49], v[56:57], v[84:85] op_sel:[0,0,0] op_sel_hi:[0,1,1]
	v_pk_fma_f32 v[86:87], v[48:49], v[56:57], v[86:87] op_sel:[1,0,0] op_sel_hi:[1,1,1]
	v_add_f32_dpp v28, v28, v28 quad_perm:[2,3,0,1] row_mask:0xf bank_mask:0xf
	v_add_f32_dpp v22, v22, v22 row_mirror row_mask:0xf bank_mask:0xf
	v_add_f32_dpp v23, v23, v23 row_mirror row_mask:0xf bank_mask:0xf
	v_pk_fma_f32 v[88:89], v[50:51], v[56:57], v[88:89] op_sel:[0,0,0] op_sel_hi:[0,1,1]
	v_pk_fma_f32 v[90:91], v[50:51], v[56:57], v[90:91] op_sel:[1,0,0] op_sel_hi:[1,1,1]
	v_cndmask_b32_e64 v32, v32, v28, s[10:11]
	v_pk_fma_f32 v[2:3], v[44:45], v[22:23], v[84:85] op_sel:[0,0,0] op_sel_hi:[0,1,1] neg_lo:[1,0,0] neg_hi:[1,0,0]
	v_pk_fma_f32 v[4:5], v[44:45], v[22:23], v[86:87] op_sel:[1,0,0] op_sel_hi:[1,1,1] neg_lo:[1,0,0] neg_hi:[1,0,0]
	v_pk_fma_f32 v[6:7], v[46:47], v[22:23], v[88:89] op_sel:[0,0,0] op_sel_hi:[0,1,1] neg_lo:[1,0,0] neg_hi:[1,0,0]
	v_pk_fma_f32 v[8:9], v[46:47], v[22:23], v[90:91] op_sel:[1,0,0] op_sel_hi:[1,1,1] neg_lo:[1,0,0] neg_hi:[1,0,0]
	s_waitcnt lgkmcnt(0)
	ds_read_b128 v[36:39], v20 offset:7168
	ds_read_b128 v[40:43], v20 offset:15360
	ds_read_b64 v[56:57], v21 offset:48128
	ds_read_b128 v[48:51], v20 offset:31744
	ds_read_b128 v[44:47], v20 offset:23552
	v_pk_mul_f32 v[22:23], v[2:3], v[60:61] op_sel:[0,0] op_sel_hi:[1,0]
	v_pk_mul_f32 v[28:29], v[2:3], v[52:53] op_sel:[0,0] op_sel_hi:[1,0]
	v_pk_fma_f32 v[22:23], v[4:5], v[60:61], v[22:23] op_sel:[0,1,0] op_sel_hi:[1,1,1]
	v_pk_fma_f32 v[28:29], v[4:5], v[52:53], v[28:29] op_sel:[0,1,0] op_sel_hi:[1,1,1]
	v_pk_fma_f32 v[22:23], v[6:7], v[62:63], v[22:23] op_sel:[0,0,0] op_sel_hi:[1,0,1]
	v_pk_fma_f32 v[28:29], v[6:7], v[54:55], v[28:29] op_sel:[0,0,0] op_sel_hi:[1,0,1]
	v_pk_fma_f32 v[22:23], v[8:9], v[62:63], v[22:23] op_sel:[0,1,0] op_sel_hi:[1,1,1]
	v_pk_fma_f32 v[28:29], v[8:9], v[54:55], v[28:29] op_sel:[0,1,0] op_sel_hi:[1,1,1]
	ds_read_b128 v[52:55], v20 offset:39936
	v_add_f32_dpp v24, v24, v24 row_ror:12 row_mask:0xf bank_mask:0x5
	v_add_f32_dpp v25, v25, v25 row_ror:4 row_mask:0xf bank_mask:0xa
	v_add_f32_dpp v22, v22, v22 quad_perm:[1,0,3,2] row_mask:0xf bank_mask:0xf
	v_add_f32_dpp v23, v23, v23 quad_perm:[1,0,3,2] row_mask:0xf bank_mask:0xf
	v_pk_mul_f32 v[84:85], v[2:3], v[64:65] op_sel:[0,0] op_sel_hi:[1,0]
	v_pk_mul_f32 v[86:87], v[4:5], v[64:65] op_sel:[0,1] op_sel_hi:[1,1]
	v_add_f32_dpp v26, v26, v26 row_ror:12 row_mask:0xf bank_mask:0x5
	v_add_f32_dpp v22, v22, v22 quad_perm:[2,3,0,1] row_mask:0xf bank_mask:0xf
	v_add_f32_dpp v23, v23, v23 quad_perm:[2,3,0,1] row_mask:0xf bank_mask:0xf
	v_pk_mul_f32 v[88:89], v[6:7], v[66:67] op_sel:[0,0] op_sel_hi:[1,0]
	v_pk_mul_f32 v[90:91], v[8:9], v[66:67] op_sel:[0,1] op_sel_hi:[1,1]
	v_add_f32_dpp v27, v27, v27 row_ror:4 row_mask:0xf bank_mask:0xa
	v_add_f32_dpp v22, v22, v22 row_half_mirror row_mask:0xf bank_mask:0xf
	v_add_f32_dpp v23, v23, v23 row_half_mirror row_mask:0xf bank_mask:0xf
	v_pk_fma_f32 v[84:85], v[72:73], v[80:81], v[84:85] op_sel:[0,0,0] op_sel_hi:[0,1,1]
	v_pk_fma_f32 v[86:87], v[72:73], v[80:81], v[86:87] op_sel:[1,0,0] op_sel_hi:[1,1,1]
	v_mov_b32_dpp v24, v25 quad_perm:[0,1,2,3] row_mask:0xf bank_mask:0xa
	v_add_f32_dpp v22, v22, v22 row_mirror row_mask:0xf bank_mask:0xf
	v_add_f32_dpp v23, v23, v23 row_mirror row_mask:0xf bank_mask:0xf
	v_pk_fma_f32 v[88:89], v[74:75], v[80:81], v[88:89] op_sel:[0,0,0] op_sel_hi:[0,1,1]
	v_pk_fma_f32 v[90:91], v[74:75], v[80:81], v[90:91] op_sel:[1,0,0] op_sel_hi:[1,1,1]
	v_mov_b32_dpp v26, v27 quad_perm:[0,1,2,3] row_mask:0xf bank_mask:0xa
	v_pk_fma_f32 v[2:3], v[68:69], v[22:23], v[84:85] op_sel:[0,0,0] op_sel_hi:[0,1,1] neg_lo:[1,0,0] neg_hi:[1,0,0]
	v_pk_fma_f32 v[4:5], v[68:69], v[22:23], v[86:87] op_sel:[1,0,0] op_sel_hi:[1,1,1] neg_lo:[1,0,0] neg_hi:[1,0,0]
	v_pk_fma_f32 v[6:7], v[70:71], v[22:23], v[88:89] op_sel:[0,0,0] op_sel_hi:[0,1,1] neg_lo:[1,0,0] neg_hi:[1,0,0]
	v_pk_fma_f32 v[8:9], v[70:71], v[22:23], v[90:91] op_sel:[1,0,0] op_sel_hi:[1,1,1] neg_lo:[1,0,0] neg_hi:[1,0,0]
	s_waitcnt lgkmcnt(0)
	ds_read_b128 v[60:63], v20 offset:7424
	ds_read_b128 v[64:67], v20 offset:15616
	ds_read_b64 v[80:81], v21 offset:48384
	ds_read_b128 v[72:75], v20 offset:32000
	ds_read_b128 v[68:71], v20 offset:23808
	v_pk_mul_f32 v[22:23], v[2:3], v[36:37] op_sel:[0,0] op_sel_hi:[1,0]
	v_pk_mul_f32 v[58:59], v[2:3], v[76:77] op_sel:[0,0] op_sel_hi:[1,0]
	v_pk_fma_f32 v[22:23], v[4:5], v[36:37], v[22:23] op_sel:[0,1,0] op_sel_hi:[1,1,1]
	v_pk_fma_f32 v[58:59], v[4:5], v[76:77], v[58:59] op_sel:[0,1,0] op_sel_hi:[1,1,1]
	v_pk_fma_f32 v[22:23], v[6:7], v[38:39], v[22:23] op_sel:[0,0,0] op_sel_hi:[1,0,1]
	v_pk_fma_f32 v[58:59], v[6:7], v[78:79], v[58:59] op_sel:[0,0,0] op_sel_hi:[1,0,1]
	v_pk_fma_f32 v[22:23], v[8:9], v[38:39], v[22:23] op_sel:[0,1,0] op_sel_hi:[1,1,1]
	v_pk_fma_f32 v[58:59], v[8:9], v[78:79], v[58:59] op_sel:[0,1,0] op_sel_hi:[1,1,1]
	ds_read_b128 v[76:79], v20 offset:40192
	v_add_f32_dpp v24, v24, v24 row_ror:8 row_mask:0xf bank_mask:0x3
	v_add_f32_dpp v26, v26, v26 row_ror:8 row_mask:0xf bank_mask:0xc
	v_add_f32_dpp v22, v22, v22 quad_perm:[1,0,3,2] row_mask:0xf bank_mask:0xf
	v_add_f32_dpp v23, v23, v23 quad_perm:[1,0,3,2] row_mask:0xf bank_mask:0xf
	v_pk_mul_f32 v[84:85], v[2:3], v[40:41] op_sel:[0,0] op_sel_hi:[1,0]
	v_pk_mul_f32 v[86:87], v[4:5], v[40:41] op_sel:[0,1] op_sel_hi:[1,1]
	v_mov_b32_dpp v24, v26 quad_perm:[0,1,2,3] row_mask:0xf bank_mask:0xc
	v_add_f32_dpp v22, v22, v22 quad_perm:[2,3,0,1] row_mask:0xf bank_mask:0xf
	v_add_f32_dpp v23, v23, v23 quad_perm:[2,3,0,1] row_mask:0xf bank_mask:0xf
	v_pk_mul_f32 v[88:89], v[6:7], v[42:43] op_sel:[0,0] op_sel_hi:[1,0]
	v_pk_mul_f32 v[90:91], v[8:9], v[42:43] op_sel:[0,1] op_sel_hi:[1,1]
	v_add_f32_dpp v24, v24, v24 quad_perm:[1,0,3,2] row_mask:0xf bank_mask:0xf
	v_add_f32_dpp v22, v22, v22 row_half_mirror row_mask:0xf bank_mask:0xf
	v_add_f32_dpp v23, v23, v23 row_half_mirror row_mask:0xf bank_mask:0xf
	v_pk_fma_f32 v[84:85], v[48:49], v[56:57], v[84:85] op_sel:[0,0,0] op_sel_hi:[0,1,1]
	v_pk_fma_f32 v[86:87], v[48:49], v[56:57], v[86:87] op_sel:[1,0,0] op_sel_hi:[1,1,1]
	v_add_f32_dpp v24, v24, v24 quad_perm:[2,3,0,1] row_mask:0xf bank_mask:0xf
	v_add_f32_dpp v22, v22, v22 row_mirror row_mask:0xf bank_mask:0xf
	v_add_f32_dpp v23, v23, v23 row_mirror row_mask:0xf bank_mask:0xf
	v_pk_fma_f32 v[88:89], v[50:51], v[56:57], v[88:89] op_sel:[0,0,0] op_sel_hi:[0,1,1]
	v_pk_fma_f32 v[90:91], v[50:51], v[56:57], v[90:91] op_sel:[1,0,0] op_sel_hi:[1,1,1]
	v_cndmask_b32_e64 v33, 0, v24, s[0:1]
	v_pk_fma_f32 v[2:3], v[44:45], v[22:23], v[84:85] op_sel:[0,0,0] op_sel_hi:[0,1,1] neg_lo:[1,0,0] neg_hi:[1,0,0]
	v_pk_fma_f32 v[4:5], v[44:45], v[22:23], v[86:87] op_sel:[1,0,0] op_sel_hi:[1,1,1] neg_lo:[1,0,0] neg_hi:[1,0,0]
	v_pk_fma_f32 v[6:7], v[46:47], v[22:23], v[88:89] op_sel:[0,0,0] op_sel_hi:[0,1,1] neg_lo:[1,0,0] neg_hi:[1,0,0]
	v_pk_fma_f32 v[8:9], v[46:47], v[22:23], v[90:91] op_sel:[1,0,0] op_sel_hi:[1,1,1] neg_lo:[1,0,0] neg_hi:[1,0,0]
	s_waitcnt lgkmcnt(0)
	ds_read_b128 v[36:39], v20 offset:7680
	ds_read_b128 v[40:43], v20 offset:15872
	ds_read_b64 v[56:57], v21 offset:48640
	ds_read_b128 v[48:51], v20 offset:32256
	ds_read_b128 v[44:47], v20 offset:24064
	v_pk_mul_f32 v[22:23], v[2:3], v[60:61] op_sel:[0,0] op_sel_hi:[1,0]
	v_pk_mul_f32 v[24:25], v[2:3], v[52:53] op_sel:[0,0] op_sel_hi:[1,0]
	v_pk_fma_f32 v[22:23], v[4:5], v[60:61], v[22:23] op_sel:[0,1,0] op_sel_hi:[1,1,1]
	v_pk_fma_f32 v[24:25], v[4:5], v[52:53], v[24:25] op_sel:[0,1,0] op_sel_hi:[1,1,1]
	v_pk_fma_f32 v[22:23], v[6:7], v[62:63], v[22:23] op_sel:[0,0,0] op_sel_hi:[1,0,1]
	v_pk_fma_f32 v[24:25], v[6:7], v[54:55], v[24:25] op_sel:[0,0,0] op_sel_hi:[1,0,1]
	v_pk_fma_f32 v[22:23], v[8:9], v[62:63], v[22:23] op_sel:[0,1,0] op_sel_hi:[1,1,1]
	v_pk_fma_f32 v[24:25], v[8:9], v[54:55], v[24:25] op_sel:[0,1,0] op_sel_hi:[1,1,1]
	ds_read_b128 v[52:55], v20 offset:40448
	v_add_f32_dpp v28, v28, v28 row_ror:12 row_mask:0xf bank_mask:0x5
	v_add_f32_dpp v29, v29, v29 row_ror:4 row_mask:0xf bank_mask:0xa
	v_add_f32_dpp v22, v22, v22 quad_perm:[1,0,3,2] row_mask:0xf bank_mask:0xf
	v_add_f32_dpp v23, v23, v23 quad_perm:[1,0,3,2] row_mask:0xf bank_mask:0xf
	v_pk_mul_f32 v[84:85], v[2:3], v[64:65] op_sel:[0,0] op_sel_hi:[1,0]
	v_pk_mul_f32 v[86:87], v[4:5], v[64:65] op_sel:[0,1] op_sel_hi:[1,1]
	v_add_f32_dpp v58, v58, v58 row_ror:12 row_mask:0xf bank_mask:0x5
	v_add_f32_dpp v22, v22, v22 quad_perm:[2,3,0,1] row_mask:0xf bank_mask:0xf
	v_add_f32_dpp v23, v23, v23 quad_perm:[2,3,0,1] row_mask:0xf bank_mask:0xf
	v_pk_mul_f32 v[88:89], v[6:7], v[66:67] op_sel:[0,0] op_sel_hi:[1,0]
	v_pk_mul_f32 v[90:91], v[8:9], v[66:67] op_sel:[0,1] op_sel_hi:[1,1]
	v_add_f32_dpp v59, v59, v59 row_ror:4 row_mask:0xf bank_mask:0xa
	v_add_f32_dpp v22, v22, v22 row_half_mirror row_mask:0xf bank_mask:0xf
	v_add_f32_dpp v23, v23, v23 row_half_mirror row_mask:0xf bank_mask:0xf
	v_pk_fma_f32 v[84:85], v[72:73], v[80:81], v[84:85] op_sel:[0,0,0] op_sel_hi:[0,1,1]
	v_pk_fma_f32 v[86:87], v[72:73], v[80:81], v[86:87] op_sel:[1,0,0] op_sel_hi:[1,1,1]
	v_mov_b32_dpp v28, v29 quad_perm:[0,1,2,3] row_mask:0xf bank_mask:0xa
	v_add_f32_dpp v22, v22, v22 row_mirror row_mask:0xf bank_mask:0xf
	v_add_f32_dpp v23, v23, v23 row_mirror row_mask:0xf bank_mask:0xf
	v_pk_fma_f32 v[88:89], v[74:75], v[80:81], v[88:89] op_sel:[0,0,0] op_sel_hi:[0,1,1]
	v_pk_fma_f32 v[90:91], v[74:75], v[80:81], v[90:91] op_sel:[1,0,0] op_sel_hi:[1,1,1]
	v_mov_b32_dpp v58, v59 quad_perm:[0,1,2,3] row_mask:0xf bank_mask:0xa
	v_pk_fma_f32 v[2:3], v[68:69], v[22:23], v[84:85] op_sel:[0,0,0] op_sel_hi:[0,1,1] neg_lo:[1,0,0] neg_hi:[1,0,0]
	v_pk_fma_f32 v[4:5], v[68:69], v[22:23], v[86:87] op_sel:[1,0,0] op_sel_hi:[1,1,1] neg_lo:[1,0,0] neg_hi:[1,0,0]
	v_pk_fma_f32 v[6:7], v[70:71], v[22:23], v[88:89] op_sel:[0,0,0] op_sel_hi:[0,1,1] neg_lo:[1,0,0] neg_hi:[1,0,0]
	v_pk_fma_f32 v[8:9], v[70:71], v[22:23], v[90:91] op_sel:[1,0,0] op_sel_hi:[1,1,1] neg_lo:[1,0,0] neg_hi:[1,0,0]
	s_waitcnt lgkmcnt(0)
	ds_read_b128 v[60:63], v20 offset:7936
	ds_read_b128 v[64:67], v20 offset:16128
	ds_read_b64 v[80:81], v21 offset:48896
	ds_read_b128 v[72:75], v20 offset:32512
	ds_read_b128 v[68:71], v20 offset:24320
	v_pk_mul_f32 v[22:23], v[2:3], v[36:37] op_sel:[0,0] op_sel_hi:[1,0]
	v_pk_mul_f32 v[26:27], v[2:3], v[76:77] op_sel:[0,0] op_sel_hi:[1,0]
	v_pk_fma_f32 v[22:23], v[4:5], v[36:37], v[22:23] op_sel:[0,1,0] op_sel_hi:[1,1,1]
	v_pk_fma_f32 v[26:27], v[4:5], v[76:77], v[26:27] op_sel:[0,1,0] op_sel_hi:[1,1,1]
	v_pk_fma_f32 v[22:23], v[6:7], v[38:39], v[22:23] op_sel:[0,0,0] op_sel_hi:[1,0,1]
	v_pk_fma_f32 v[26:27], v[6:7], v[78:79], v[26:27] op_sel:[0,0,0] op_sel_hi:[1,0,1]
	v_pk_fma_f32 v[22:23], v[8:9], v[38:39], v[22:23] op_sel:[0,1,0] op_sel_hi:[1,1,1]
	v_pk_fma_f32 v[26:27], v[8:9], v[78:79], v[26:27] op_sel:[0,1,0] op_sel_hi:[1,1,1]
	ds_read_b128 v[76:79], v20 offset:40704
	v_add_f32_dpp v28, v28, v28 row_ror:8 row_mask:0xf bank_mask:0x3
	v_add_f32_dpp v58, v58, v58 row_ror:8 row_mask:0xf bank_mask:0xc
	v_add_f32_dpp v22, v22, v22 quad_perm:[1,0,3,2] row_mask:0xf bank_mask:0xf
	v_add_f32_dpp v23, v23, v23 quad_perm:[1,0,3,2] row_mask:0xf bank_mask:0xf
	v_pk_mul_f32 v[84:85], v[2:3], v[40:41] op_sel:[0,0] op_sel_hi:[1,0]
	v_pk_mul_f32 v[86:87], v[4:5], v[40:41] op_sel:[0,1] op_sel_hi:[1,1]
	v_mov_b32_dpp v28, v58 quad_perm:[0,1,2,3] row_mask:0xf bank_mask:0xc
	v_add_f32_dpp v22, v22, v22 quad_perm:[2,3,0,1] row_mask:0xf bank_mask:0xf
	v_add_f32_dpp v23, v23, v23 quad_perm:[2,3,0,1] row_mask:0xf bank_mask:0xf
	v_pk_mul_f32 v[88:89], v[6:7], v[42:43] op_sel:[0,0] op_sel_hi:[1,0]
	v_pk_mul_f32 v[90:91], v[8:9], v[42:43] op_sel:[0,1] op_sel_hi:[1,1]
	v_add_f32_dpp v28, v28, v28 quad_perm:[1,0,3,2] row_mask:0xf bank_mask:0xf
	v_add_f32_dpp v22, v22, v22 row_half_mirror row_mask:0xf bank_mask:0xf
	v_add_f32_dpp v23, v23, v23 row_half_mirror row_mask:0xf bank_mask:0xf
	v_pk_fma_f32 v[84:85], v[48:49], v[56:57], v[84:85] op_sel:[0,0,0] op_sel_hi:[0,1,1]
	v_pk_fma_f32 v[86:87], v[48:49], v[56:57], v[86:87] op_sel:[1,0,0] op_sel_hi:[1,1,1]
	v_add_f32_dpp v28, v28, v28 quad_perm:[2,3,0,1] row_mask:0xf bank_mask:0xf
	v_add_f32_dpp v22, v22, v22 row_mirror row_mask:0xf bank_mask:0xf
	v_add_f32_dpp v23, v23, v23 row_mirror row_mask:0xf bank_mask:0xf
	v_pk_fma_f32 v[88:89], v[50:51], v[56:57], v[88:89] op_sel:[0,0,0] op_sel_hi:[0,1,1]
	v_pk_fma_f32 v[90:91], v[50:51], v[56:57], v[90:91] op_sel:[1,0,0] op_sel_hi:[1,1,1]
	v_cndmask_b32_e64 v33, v33, v28, s[6:7]
	v_pk_fma_f32 v[2:3], v[44:45], v[22:23], v[84:85] op_sel:[0,0,0] op_sel_hi:[0,1,1] neg_lo:[1,0,0] neg_hi:[1,0,0]
	v_pk_fma_f32 v[4:5], v[44:45], v[22:23], v[86:87] op_sel:[1,0,0] op_sel_hi:[1,1,1] neg_lo:[1,0,0] neg_hi:[1,0,0]
	v_pk_fma_f32 v[6:7], v[46:47], v[22:23], v[88:89] op_sel:[0,0,0] op_sel_hi:[0,1,1] neg_lo:[1,0,0] neg_hi:[1,0,0]
	v_pk_fma_f32 v[8:9], v[46:47], v[22:23], v[90:91] op_sel:[1,0,0] op_sel_hi:[1,1,1] neg_lo:[1,0,0] neg_hi:[1,0,0]
	s_waitcnt lgkmcnt(0)
	v_pk_mul_f32 v[22:23], v[2:3], v[60:61] op_sel:[0,0] op_sel_hi:[1,0]
	v_pk_mul_f32 v[28:29], v[2:3], v[52:53] op_sel:[0,0] op_sel_hi:[1,0]
	v_pk_fma_f32 v[22:23], v[4:5], v[60:61], v[22:23] op_sel:[0,1,0] op_sel_hi:[1,1,1]
	v_pk_fma_f32 v[28:29], v[4:5], v[52:53], v[28:29] op_sel:[0,1,0] op_sel_hi:[1,1,1]
	v_pk_fma_f32 v[22:23], v[6:7], v[62:63], v[22:23] op_sel:[0,0,0] op_sel_hi:[1,0,1]
	v_pk_fma_f32 v[28:29], v[6:7], v[54:55], v[28:29] op_sel:[0,0,0] op_sel_hi:[1,0,1]
	v_pk_fma_f32 v[22:23], v[8:9], v[62:63], v[22:23] op_sel:[0,1,0] op_sel_hi:[1,1,1]
	v_pk_fma_f32 v[28:29], v[8:9], v[54:55], v[28:29] op_sel:[0,1,0] op_sel_hi:[1,1,1]
	v_add_f32_dpp v24, v24, v24 row_ror:12 row_mask:0xf bank_mask:0x5
	v_add_f32_dpp v25, v25, v25 row_ror:4 row_mask:0xf bank_mask:0xa
	v_add_f32_dpp v22, v22, v22 quad_perm:[1,0,3,2] row_mask:0xf bank_mask:0xf
	v_add_f32_dpp v23, v23, v23 quad_perm:[1,0,3,2] row_mask:0xf bank_mask:0xf
	v_pk_mul_f32 v[84:85], v[2:3], v[64:65] op_sel:[0,0] op_sel_hi:[1,0]
	v_pk_mul_f32 v[86:87], v[4:5], v[64:65] op_sel:[0,1] op_sel_hi:[1,1]
	v_add_f32_dpp v26, v26, v26 row_ror:12 row_mask:0xf bank_mask:0x5
	v_add_f32_dpp v22, v22, v22 quad_perm:[2,3,0,1] row_mask:0xf bank_mask:0xf
	v_add_f32_dpp v23, v23, v23 quad_perm:[2,3,0,1] row_mask:0xf bank_mask:0xf
	v_pk_mul_f32 v[88:89], v[6:7], v[66:67] op_sel:[0,0] op_sel_hi:[1,0]
	v_pk_mul_f32 v[90:91], v[8:9], v[66:67] op_sel:[0,1] op_sel_hi:[1,1]
	v_add_f32_dpp v27, v27, v27 row_ror:4 row_mask:0xf bank_mask:0xa
	v_add_f32_dpp v22, v22, v22 row_half_mirror row_mask:0xf bank_mask:0xf
	v_add_f32_dpp v23, v23, v23 row_half_mirror row_mask:0xf bank_mask:0xf
	v_pk_fma_f32 v[84:85], v[72:73], v[80:81], v[84:85] op_sel:[0,0,0] op_sel_hi:[0,1,1]
	v_pk_fma_f32 v[86:87], v[72:73], v[80:81], v[86:87] op_sel:[1,0,0] op_sel_hi:[1,1,1]
	v_mov_b32_dpp v24, v25 quad_perm:[0,1,2,3] row_mask:0xf bank_mask:0xa
	v_add_f32_dpp v22, v22, v22 row_mirror row_mask:0xf bank_mask:0xf
	v_add_f32_dpp v23, v23, v23 row_mirror row_mask:0xf bank_mask:0xf
	v_pk_fma_f32 v[88:89], v[74:75], v[80:81], v[88:89] op_sel:[0,0,0] op_sel_hi:[0,1,1]
	v_pk_fma_f32 v[90:91], v[74:75], v[80:81], v[90:91] op_sel:[1,0,0] op_sel_hi:[1,1,1]
	v_mov_b32_dpp v26, v27 quad_perm:[0,1,2,3] row_mask:0xf bank_mask:0xa
	v_pk_fma_f32 v[2:3], v[68:69], v[22:23], v[84:85] op_sel:[0,0,0] op_sel_hi:[0,1,1] neg_lo:[1,0,0] neg_hi:[1,0,0]
	v_pk_fma_f32 v[4:5], v[68:69], v[22:23], v[86:87] op_sel:[1,0,0] op_sel_hi:[1,1,1] neg_lo:[1,0,0] neg_hi:[1,0,0]
	v_pk_fma_f32 v[6:7], v[70:71], v[22:23], v[88:89] op_sel:[0,0,0] op_sel_hi:[0,1,1] neg_lo:[1,0,0] neg_hi:[1,0,0]
	v_pk_fma_f32 v[8:9], v[70:71], v[22:23], v[90:91] op_sel:[1,0,0] op_sel_hi:[1,1,1] neg_lo:[1,0,0] neg_hi:[1,0,0]
	s_waitcnt lgkmcnt(0)
	v_pk_mul_f32 v[58:59], v[2:3], v[76:77] op_sel:[0,0] op_sel_hi:[1,0]
	v_pk_fma_f32 v[58:59], v[4:5], v[76:77], v[58:59] op_sel:[0,1,0] op_sel_hi:[1,1,1]
	v_pk_fma_f32 v[58:59], v[6:7], v[78:79], v[58:59] op_sel:[0,0,0] op_sel_hi:[1,0,1]
	v_pk_fma_f32 v[58:59], v[8:9], v[78:79], v[58:59] op_sel:[0,1,0] op_sel_hi:[1,1,1]
	v_add_f32_dpp v24, v24, v24 row_ror:8 row_mask:0xf bank_mask:0x3
	v_add_f32_dpp v26, v26, v26 row_ror:8 row_mask:0xf bank_mask:0xc
	s_nop 1
	v_mov_b32_dpp v24, v26 quad_perm:[0,1,2,3] row_mask:0xf bank_mask:0xc
	s_nop 1
	v_add_f32_dpp v24, v24, v24 quad_perm:[1,0,3,2] row_mask:0xf bank_mask:0xf
	s_nop 1
	v_add_f32_dpp v24, v24, v24 quad_perm:[2,3,0,1] row_mask:0xf bank_mask:0xf
	v_cndmask_b32_e64 v33, v33, v24, s[8:9]
	v_add_f32_dpp v28, v28, v28 row_ror:12 row_mask:0xf bank_mask:0x5
	v_add_f32_dpp v29, v29, v29 row_ror:4 row_mask:0xf bank_mask:0xa
	v_add_f32_dpp v58, v58, v58 row_ror:12 row_mask:0xf bank_mask:0x5
	v_add_f32_dpp v59, v59, v59 row_ror:4 row_mask:0xf bank_mask:0xa
	v_mov_b32_dpp v28, v29 quad_perm:[0,1,2,3] row_mask:0xf bank_mask:0xa
	s_nop 0
	v_mov_b32_dpp v58, v59 quad_perm:[0,1,2,3] row_mask:0xf bank_mask:0xa
	v_add_f32_dpp v28, v28, v28 row_ror:8 row_mask:0xf bank_mask:0x3
	s_nop 0
	v_add_f32_dpp v58, v58, v58 row_ror:8 row_mask:0xf bank_mask:0xc
	s_nop 1
	v_mov_b32_dpp v28, v58 quad_perm:[0,1,2,3] row_mask:0xf bank_mask:0xc
	s_nop 1
	v_add_f32_dpp v28, v28, v28 quad_perm:[1,0,3,2] row_mask:0xf bank_mask:0xf
	s_nop 1
	v_add_f32_dpp v28, v28, v28 quad_perm:[2,3,0,1] row_mask:0xf bank_mask:0xf
	v_cndmask_b32_e64 v33, v33, v28, s[10:11]
	v_lshl_add_u32 v35, s23, 12, v11
	s_add_i32 s22, s22, 1
	ds_write2st64_b32 v35, v30, v31 offset1:4
	ds_write2st64_b32 v35, v32, v33 offset0:8 offset1:12
	s_cmp_eq_u32 s22, 64
	s_waitcnt lgkmcnt(0)
	s_barrier
	s_cbranch_scc0 .LBB0_1750
	s_setprio 0
	s_lshl_b32 s0, s18, 4
	s_or_b32 s0, s0, s26
	s_ashr_i32 s1, s0, 31
	s_lshl_b64 s[0:1], s[0:1], 6
	s_lshl_b32 s2, s27, 5
	s_or_b32 s0, s0, s2
	v_or_b32_e32 v12, s0, v1
	v_mov_b32_e32 v13, s1
	v_lshlrev_b64 v[12:13], 8, v[12:13]
	v_lshl_add_u64 v[12:13], s[82:83], 0, v[12:13]
	v_mov_b32_e32 v11, 0
	v_lshl_add_u64 v[10:11], v[12:13], 0, v[10:11]
	s_mov_b64 s[0:1], 0x4100000
	v_lshl_add_u64 v[12:13], v[10:11], 0, s[0:1]
	v_add_co_u32_e32 v10, vcc, 0x4100000, v10
	s_nop 1
	v_addc_co_u32_e32 v11, vcc, 0, v11, vcc
	v_mov_b32_e32 v14, v2
	v_mov_b32_e32 v15, v4
	v_mov_b32_e32 v16, v6
	v_mov_b32_e32 v17, v8
	v_mov_b32_e32 v18, v3
	v_mov_b32_e32 v19, v5
	v_mov_b32_e32 v20, v7
	v_mov_b32_e32 v21, v9
	global_store_dwordx4 v[10:11], v[14:17], off
	global_store_dwordx4 v[12:13], v[18:21], off offset:256
